# memory cross-attention slab loops: next slab's q loads issued before the 16 output stores, counted vmcnt at the loop top (stores no longer waited on), on top of the previous best
# baseline (speedup 1.0000x reference)
.LBB0_640:
	global_load_dwordx4 v[120:123], v[0:1], off
	v_lshl_add_u64 v[0:1], v[0:1], 0, s[6:7]
	global_load_dwordx4 v[124:127], v[0:1], off
	v_lshl_add_u64 v[0:1], v[0:1], 0, s[6:7]
	global_load_dwordx4 v[128:131], v[0:1], off
	v_lshl_add_u64 v[0:1], v[0:1], 0, s[6:7]
	global_load_dwordx4 v[132:135], v[0:1], off
	v_lshl_add_u64 v[0:1], v[0:1], 0, s[6:7]
	v_mov_b32_e32 v136, v2
	v_add_u32_e32 v2, 0x8400, v2
	s_waitcnt vmcnt(0)
	ds_write_b128 v116, v[100:103]
	ds_write_b128 v116, v[104:107] offset:9216
	ds_write_b128 v116, v[108:111] offset:18432
	ds_write_b128 v116, v[112:115] offset:27648
	ds_write_b128 v136, v[120:123]
	ds_write_b128 v136, v[124:127] offset:8448
	ds_write_b128 v136, v[128:131] offset:16896
	ds_write_b128 v136, v[132:135] offset:25344
	s_or_b64 exec, exec, s[4:5]
	v_lshrrev_b32_e32 v0, 6, v176
	s_and_b32 s4, s90, -8
	v_add_u32_e32 v96, s4, v0
	s_movk_i32 s4, 0x400
	v_cmp_gt_i32_e32 vcc, s4, v96
	s_waitcnt lgkmcnt(0)
	s_barrier
	s_and_saveexec_b64 s[4:5], vcc
	s_cbranch_execz .LBB0_644
	v_bfe_u32 v2, v176, 4, 2
	v_and_b32_e32 v1, 15, v176
	s_movk_i32 s6, 0x2100
	v_mov_b32_e32 v3, 0x11400
	v_mad_u32_u24 v0, v0, s6, v3
	v_lshlrev_b32_e32 v3, 1, v1
	v_lshlrev_b32_e32 v6, 4, v2
	s_movk_i32 s6, 0x90
	v_or_b32_e32 v4, v0, v3
	v_mad_u32_u24 v105, v1, s6, v6
	s_movk_i32 s6, 0x840
	v_mad_u32_u24 v109, v2, s6, v4
	s_lshl_b32 s6, s90, 23
	s_and_b32 s6, s6, 0x2000000
	s_add_u32 s2, s2, s8
	v_mul_u32_u24_e32 v5, 0x210, v1
	v_mov_b32_e32 v99, 0
	s_addc_u32 s3, s3, 0
	v_add3_u32 v104, v0, v5, v6
	v_or_b32_e32 v0, 16, v1
	v_mov_b32_e32 v97, v99
	s_add_u32 s2, s2, s6
	v_mul_u32_u24_e32 v4, 0x210, v0
	v_lshl_or_b32 v98, v1, 11, v6
	s_mov_b32 s35, 0
	v_lshlrev_b64 v[0:1], 15, v[96:97]
	s_addc_u32 s3, s3, 0
	v_add_u32_e32 v106, 0x900, v105
	v_add_u32_e32 v107, 0x1200, v105
	v_add_u32_e32 v108, 0x1b00, v105
	v_lshl_add_u64 v[100:101], s[2:3], 0, v[0:1]
	s_lshl_b64 s[2:3], s[34:35], 15
	v_lshl_or_b32 v102, v2, 13, v3
	v_mov_b32_e32 v103, v99
	s_mov_b64 s[6:7], 0
	s_mov_b32 s8, 0x1b400000
	s_movk_i32 s9, 0x7fff
	v_add_u32_e32 v97, v6, v5
	v_add_u32_e32 v110, v6, v4
	s_mov_b32 s10, 0x1b401000
	s_movk_i32 s11, 0x3ff
	v_lshl_add_u64 v[240:241], v[100:101], 0, v[98:99]
	v_add_co_u32_e32 v240, vcc, 0x1b400000, v240
	s_nop 1
	v_addc_co_u32_e32 v241, vcc, 0, v241, vcc
	global_load_dwordx4 v[232:235], v[240:241], off offset:1536
	global_load_dwordx4 v[236:239], v[240:241], off offset:1600
	s_waitcnt vmcnt(0)
.LBB0_643:
	ds_read_b128 v[0:3], v105
	ds_read_b128 v[4:7], v105 offset:64
	ds_read_b128 v[12:15], v106
	ds_read_b128 v[16:19], v106 offset:64
	ds_read_b128 v[20:23], v107
	ds_read_b128 v[24:27], v107 offset:64
	ds_read_b128 v[28:31], v108
	ds_read_b128 v[68:71], v108 offset:64
	ds_read_b128 v[36:39], v105 offset:9216
	ds_read_b128 v[112:115], v105 offset:9280
	v_mov_b32_e32 v111, 0
	v_add_u32_e32 v96, s34, v96
	s_waitcnt vmcnt(16) lgkmcnt(0)
	v_mov_b32_e32 v8, v232
	v_mov_b32_e32 v9, v233
	v_mov_b32_e32 v10, v234
	v_mov_b32_e32 v11, v235
	v_mov_b32_e32 v32, v236
	v_mov_b32_e32 v33, v237
	v_mov_b32_e32 v34, v238
	v_mov_b32_e32 v35, v239
	s_nop 1
	v_mfma_f32_16x16x32_bf16 v[116:119], v[8:11], v[36:39], 0
	ds_read_b128 v[36:39], v105 offset:11520
	ds_read_b128 v[120:123], v105 offset:11584
	s_waitcnt lgkmcnt(1)
	v_mfma_f32_16x16x32_bf16 v[124:127], v[8:11], v[36:39], 0
	ds_read_b128 v[36:39], v105 offset:13824
	ds_read_b128 v[128:131], v105 offset:13888
	s_waitcnt lgkmcnt(1)
	v_mfma_f32_16x16x32_bf16 v[132:135], v[8:11], v[36:39], 0
	ds_read_b128 v[36:39], v105 offset:16128
	ds_read_b128 v[136:139], v105 offset:16192
	s_waitcnt lgkmcnt(1)
	v_mfma_f32_16x16x32_bf16 v[140:143], v[8:11], v[36:39], 0
	ds_read_b128 v[36:39], v105 offset:18432
	ds_read_b128 v[144:147], v105 offset:18496
	s_waitcnt lgkmcnt(1)
	v_mfma_f32_16x16x32_bf16 v[148:151], v[8:11], v[36:39], 0
	ds_read_b128 v[36:39], v105 offset:20736
	ds_read_b128 v[72:75], v105 offset:20800
	s_waitcnt lgkmcnt(1)
	v_mfma_f32_16x16x32_bf16 v[92:95], v[8:11], v[36:39], 0
	ds_read_b128 v[36:39], v105 offset:23040
	ds_read_b128 v[76:79], v105 offset:23104
	s_waitcnt lgkmcnt(1)
	v_mfma_f32_16x16x32_bf16 v[88:91], v[8:11], v[36:39], 0
	ds_read_b128 v[36:39], v105 offset:25344
	ds_read_b128 v[80:83], v105 offset:25408
	v_mfma_f32_16x16x32_bf16 v[0:3], v[8:11], v[0:3], 0
	v_mfma_f32_16x16x32_bf16 v[12:15], v[8:11], v[12:15], 0
	s_waitcnt lgkmcnt(1)
	v_mfma_f32_16x16x32_bf16 v[84:87], v[8:11], v[36:39], 0
	ds_read_b128 v[40:43], v105 offset:27648
	ds_read_b128 v[36:39], v105 offset:27712
	ds_read_b128 v[48:51], v105 offset:29952
	ds_read_b128 v[44:47], v105 offset:30016
	ds_read_b128 v[56:59], v105 offset:32256
	ds_read_b128 v[52:55], v105 offset:32320
	v_mfma_f32_16x16x32_bf16 v[20:23], v[8:11], v[20:23], 0
	ds_read_b128 v[64:67], v105 offset:34560
	ds_read_b128 v[60:63], v105 offset:34624
	v_mfma_f32_16x16x32_bf16 v[28:31], v[8:11], v[28:31], 0
	s_waitcnt lgkmcnt(5)
	v_mfma_f32_16x16x32_bf16 v[48:51], v[8:11], v[48:51], 0
	s_waitcnt lgkmcnt(3)
	v_mfma_f32_16x16x32_bf16 v[56:59], v[8:11], v[56:59], 0
	v_mfma_f32_16x16x32_bf16 v[0:3], v[32:35], v[4:7], v[0:3]
	v_mfma_f32_16x16x32_bf16 v[4:7], v[32:35], v[16:19], v[12:15]
	v_mfma_f32_16x16x32_bf16 v[40:43], v[8:11], v[40:43], 0
	s_waitcnt lgkmcnt(1)
	v_mfma_f32_16x16x32_bf16 v[64:67], v[8:11], v[64:67], 0
	v_mfma_f32_16x16x32_bf16 v[8:11], v[32:35], v[24:27], v[20:23]
	v_mfma_f32_16x16x32_bf16 v[12:15], v[32:35], v[68:71], v[28:31]
	v_mfma_f32_16x16x32_bf16 v[16:19], v[32:35], v[112:115], v[116:119]
	v_mov_b32_e32 v114, 0
	v_mov_b32_e32 v113, 0
	v_mov_b32_e32 v112, 0
	v_mfma_f32_16x16x32_bf16 v[20:23], v[32:35], v[120:123], v[124:127]
	v_mov_b32_e32 v118, 0
	v_mov_b32_e32 v119, 0
	v_mov_b32_e32 v117, 0
	v_mfma_f32_16x16x32_bf16 v[24:27], v[32:35], v[128:131], v[132:135]
	v_mov_b32_e32 v116, 0
	v_mov_b32_e32 v115, 0
	v_mfma_f32_16x16x32_bf16 v[28:31], v[32:35], v[136:139], v[140:143]
	v_mfma_f32_16x16x32_bf16 v[44:47], v[32:35], v[44:47], v[48:51]
	v_mfma_f32_16x16x32_bf16 v[48:51], v[32:35], v[52:55], v[56:59]
	v_max_f32_e32 v52, v4, v4
	v_max_f32_e32 v53, v0, v0
	v_max_f32_e32 v54, v5, v5
	v_max_f32_e32 v55, v1, v1
	v_max_f32_e32 v56, v6, v6
	v_max_f32_e32 v57, v2, v2
	v_max_f32_e32 v58, v7, v7
	v_max_f32_e32 v59, v3, v3
	v_mfma_f32_16x16x32_bf16 v[68:71], v[32:35], v[144:147], v[148:151]
	v_max_f32_e32 v52, v53, v52
	v_max_f32_e32 v53, v55, v54
	v_max_f32_e32 v54, v57, v56
	v_mfma_f32_16x16x32_bf16 v[72:75], v[32:35], v[72:75], v[92:95]
	v_max_f32_e32 v55, v59, v58
	v_max3_f32 v52, v52, v8, v12
	v_max3_f32 v53, v53, v9, v13
	v_mfma_f32_16x16x32_bf16 v[76:79], v[32:35], v[76:79], v[88:91]
	v_max3_f32 v54, v54, v10, v14
	v_max3_f32 v55, v55, v11, v15
	v_max3_f32 v52, v52, v16, v20
	v_mfma_f32_16x16x32_bf16 v[80:83], v[32:35], v[80:83], v[84:87]
	v_max3_f32 v53, v53, v17, v21
	v_max3_f32 v54, v54, v18, v22
	v_max3_f32 v55, v55, v19, v23
	v_mfma_f32_16x16x32_bf16 v[40:43], v[32:35], v[36:39], v[40:43]
	v_max3_f32 v52, v52, v24, v28
	v_max3_f32 v53, v53, v25, v29
	v_max3_f32 v54, v54, v26, v30
	s_waitcnt lgkmcnt(0)
	v_mfma_f32_16x16x32_bf16 v[32:35], v[32:35], v[60:63], v[64:67]
	v_max3_f32 v55, v55, v27, v31
	v_max3_f32 v52, v52, v68, v72
	v_max3_f32 v53, v53, v69, v73
	v_max3_f32 v54, v54, v70, v74
	v_max3_f32 v55, v55, v71, v75
	v_max3_f32 v52, v52, v76, v80
	v_max3_f32 v53, v53, v77, v81
	v_max3_f32 v54, v54, v78, v82
	v_max3_f32 v55, v55, v79, v83
	v_max3_f32 v52, v52, v40, v44
	v_max3_f32 v53, v53, v41, v45
	v_max3_f32 v54, v54, v42, v46
	v_max3_f32 v55, v55, v43, v47
	v_mov_b32_e32 v88, 0
	v_max3_f32 v52, v52, v48, v32
	v_max3_f32 v53, v53, v49, v33
	v_max3_f32 v54, v54, v50, v34
	v_max3_f32 v55, v55, v51, v35
	v_mov_b32_dpp v114, v52 row_ror:8 row_mask:0xf bank_mask:0xf
	v_mov_b32_dpp v118, v53 row_ror:8 row_mask:0xf bank_mask:0xf
	v_mov_b32_dpp v119, v54 row_ror:8 row_mask:0xf bank_mask:0xf
	v_mov_b32_dpp v88, v55 row_ror:8 row_mask:0xf bank_mask:0xf
	v_max_f32_e32 v56, v114, v114
	v_max_f32_e32 v57, v118, v118
	v_max_f32_e32 v58, v119, v119
	v_max_f32_e32 v59, v88, v88
	v_mov_b32_e32 v92, 0
	v_mov_b32_e32 v89, 0
	v_max_f32_e32 v52, v52, v56
	v_max_f32_e32 v53, v53, v57
	v_max_f32_e32 v54, v54, v58
	v_max_f32_e32 v55, v55, v59
	v_mov_b32_dpp v113, v52 row_ror:4 row_mask:0xf bank_mask:0xf
	v_mov_b32_dpp v117, v53 row_ror:4 row_mask:0xf bank_mask:0xf
	v_mov_b32_dpp v92, v54 row_ror:4 row_mask:0xf bank_mask:0xf
	v_mov_b32_dpp v89, v55 row_ror:4 row_mask:0xf bank_mask:0xf
	v_max_f32_e32 v56, v113, v113
	v_max_f32_e32 v57, v117, v117
	v_max_f32_e32 v58, v92, v92
	v_max_f32_e32 v59, v89, v89
	v_mov_b32_e32 v93, 0
	v_mov_b32_e32 v90, 0
	v_max_f32_e32 v52, v52, v56
	v_max_f32_e32 v53, v53, v57
	v_max_f32_e32 v54, v54, v58
	v_max_f32_e32 v55, v55, v59
	v_mov_b32_dpp v112, v52 row_ror:2 row_mask:0xf bank_mask:0xf
	v_mov_b32_dpp v116, v53 row_ror:2 row_mask:0xf bank_mask:0xf
	v_mov_b32_dpp v93, v54 row_ror:2 row_mask:0xf bank_mask:0xf
	v_mov_b32_dpp v90, v55 row_ror:2 row_mask:0xf bank_mask:0xf
	v_max_f32_e32 v56, v112, v112
	v_max_f32_e32 v57, v116, v116
	v_max_f32_e32 v58, v93, v93
	v_max_f32_e32 v59, v90, v90
	v_mov_b32_e32 v94, 0
	v_mov_b32_e32 v86, 0
	v_max_f32_e32 v52, v52, v56
	v_max_f32_e32 v53, v53, v57
	v_max_f32_e32 v54, v54, v58
	v_max_f32_e32 v55, v55, v59
	v_mov_b32_dpp v111, v52 row_ror:1 row_mask:0xf bank_mask:0xf
	v_mov_b32_dpp v115, v53 row_ror:1 row_mask:0xf bank_mask:0xf
	v_mov_b32_dpp v94, v54 row_ror:1 row_mask:0xf bank_mask:0xf
	v_mov_b32_dpp v86, v55 row_ror:1 row_mask:0xf bank_mask:0xf
	v_max_f32_e32 v56, v111, v111
	v_max_f32_e32 v57, v115, v115
	v_max_f32_e32 v58, v94, v94
	v_max_f32_e32 v59, v86, v86
	v_max_f32_e32 v52, v52, v56
	v_max_f32_e32 v53, v53, v57
	v_max_f32_e32 v54, v54, v58
	v_max_f32_e32 v55, v55, v59
	v_sub_f32_e32 v0, v0, v52
	v_sub_f32_e32 v4, v4, v52
	v_sub_f32_e32 v8, v8, v52
	v_sub_f32_e32 v12, v12, v52
	v_sub_f32_e32 v16, v16, v52
	v_sub_f32_e32 v20, v20, v52
	v_sub_f32_e32 v24, v24, v52
	v_sub_f32_e32 v28, v28, v52
	v_sub_f32_e32 v56, v68, v52
	v_sub_f32_e32 v57, v72, v52
	v_sub_f32_e32 v58, v76, v52
	v_sub_f32_e32 v59, v80, v52
	v_sub_f32_e32 v40, v40, v52
	v_sub_f32_e32 v44, v44, v52
	v_sub_f32_e32 v48, v48, v52
	v_sub_f32_e32 v32, v32, v52
	v_sub_f32_e32 v1, v1, v53
	v_sub_f32_e32 v5, v5, v53
	v_sub_f32_e32 v9, v9, v53
	v_sub_f32_e32 v13, v13, v53
	v_sub_f32_e32 v17, v17, v53
	v_sub_f32_e32 v21, v21, v53
	v_sub_f32_e32 v29, v29, v53
	v_sub_f32_e32 v52, v69, v53
	v_sub_f32_e32 v60, v73, v53
	v_sub_f32_e32 v61, v77, v53
	v_sub_f32_e32 v62, v81, v53
	v_sub_f32_e32 v41, v41, v53
	v_sub_f32_e32 v45, v45, v53
	v_sub_f32_e32 v33, v33, v53
	v_sub_f32_e32 v2, v2, v54
	v_sub_f32_e32 v10, v10, v54
	v_sub_f32_e32 v18, v18, v54
	v_sub_f32_e32 v22, v22, v54
	v_sub_f32_e32 v63, v74, v54
	v_sub_f32_e32 v64, v78, v54
	v_sub_f32_e32 v65, v82, v54
	v_sub_f32_e32 v3, v3, v55
	v_sub_f32_e32 v11, v11, v55
	v_sub_f32_e32 v25, v25, v53
	v_sub_f32_e32 v49, v49, v53
	v_sub_f32_e32 v6, v6, v54
	v_sub_f32_e32 v14, v14, v54
	v_sub_f32_e32 v26, v26, v54
	v_sub_f32_e32 v30, v30, v54
	v_sub_f32_e32 v53, v70, v54
	v_sub_f32_e32 v42, v42, v54
	v_sub_f32_e32 v46, v46, v54
	v_sub_f32_e32 v50, v50, v54
	v_sub_f32_e32 v34, v34, v54
	v_sub_f32_e32 v7, v7, v55
	v_sub_f32_e32 v15, v15, v55
	v_sub_f32_e32 v19, v19, v55
	v_sub_f32_e32 v23, v23, v55
	v_sub_f32_e32 v27, v27, v55
	v_sub_f32_e32 v31, v31, v55
	v_sub_f32_e32 v54, v71, v55
	v_sub_f32_e32 v66, v75, v55
	v_sub_f32_e32 v67, v79, v55
	v_sub_f32_e32 v68, v83, v55
	v_sub_f32_e32 v43, v43, v55
	v_sub_f32_e32 v47, v47, v55
	v_sub_f32_e32 v51, v51, v55
	v_sub_f32_e32 v35, v35, v55
	v_mul_f32_e32 v0, 0x3fb8aa3b, v0
	v_mul_f32_e32 v4, 0x3fb8aa3b, v4
	v_mul_f32_e32 v8, 0x3fb8aa3b, v8
	v_mul_f32_e32 v12, 0x3fb8aa3b, v12
	v_mul_f32_e32 v16, 0x3fb8aa3b, v16
	v_mul_f32_e32 v20, 0x3fb8aa3b, v20
	v_mul_f32_e32 v24, 0x3fb8aa3b, v24
	v_mul_f32_e32 v28, 0x3fb8aa3b, v28
	v_mul_f32_e32 v55, 0x3fb8aa3b, v56
	v_mul_f32_e32 v56, 0x3fb8aa3b, v57
	v_mul_f32_e32 v57, 0x3fb8aa3b, v58
	v_mul_f32_e32 v58, 0x3fb8aa3b, v59
	v_mul_f32_e32 v40, 0x3fb8aa3b, v40
	v_mul_f32_e32 v44, 0x3fb8aa3b, v44
	v_mul_f32_e32 v48, 0x3fb8aa3b, v48
	v_mul_f32_e32 v32, 0x3fb8aa3b, v32
	v_mul_f32_e32 v1, 0x3fb8aa3b, v1
	v_mul_f32_e32 v5, 0x3fb8aa3b, v5
	v_mul_f32_e32 v9, 0x3fb8aa3b, v9
	v_mul_f32_e32 v13, 0x3fb8aa3b, v13
	v_mul_f32_e32 v17, 0x3fb8aa3b, v17
	v_mul_f32_e32 v21, 0x3fb8aa3b, v21
	v_mul_f32_e32 v29, 0x3fb8aa3b, v29
	v_mul_f32_e32 v52, 0x3fb8aa3b, v52
	v_mul_f32_e32 v59, 0x3fb8aa3b, v60
	v_mul_f32_e32 v60, 0x3fb8aa3b, v61
	v_mul_f32_e32 v61, 0x3fb8aa3b, v62
	v_mul_f32_e32 v41, 0x3fb8aa3b, v41
	v_mul_f32_e32 v45, 0x3fb8aa3b, v45
	v_mul_f32_e32 v33, 0x3fb8aa3b, v33
	v_mul_f32_e32 v2, 0x3fb8aa3b, v2
	v_mul_f32_e32 v10, 0x3fb8aa3b, v10
	v_mul_f32_e32 v18, 0x3fb8aa3b, v18
	v_mul_f32_e32 v22, 0x3fb8aa3b, v22
	v_mul_f32_e32 v62, 0x3fb8aa3b, v63
	v_mul_f32_e32 v63, 0x3fb8aa3b, v64
	v_mul_f32_e32 v64, 0x3fb8aa3b, v65
	v_mul_f32_e32 v3, 0x3fb8aa3b, v3
	v_mul_f32_e32 v11, 0x3fb8aa3b, v11
	v_mul_f32_e32 v25, 0x3fb8aa3b, v25
	v_mul_f32_e32 v49, 0x3fb8aa3b, v49
	v_mul_f32_e32 v6, 0x3fb8aa3b, v6
	v_mul_f32_e32 v14, 0x3fb8aa3b, v14
	v_mul_f32_e32 v26, 0x3fb8aa3b, v26
	v_mul_f32_e32 v30, 0x3fb8aa3b, v30
	v_mul_f32_e32 v53, 0x3fb8aa3b, v53
	v_mul_f32_e32 v42, 0x3fb8aa3b, v42
	v_mul_f32_e32 v46, 0x3fb8aa3b, v46
	v_mul_f32_e32 v50, 0x3fb8aa3b, v50
	v_mul_f32_e32 v34, 0x3fb8aa3b, v34
	v_mul_f32_e32 v7, 0x3fb8aa3b, v7
	v_mul_f32_e32 v15, 0x3fb8aa3b, v15
	v_mul_f32_e32 v19, 0x3fb8aa3b, v19
	v_mul_f32_e32 v23, 0x3fb8aa3b, v23
	v_mul_f32_e32 v27, 0x3fb8aa3b, v27
	v_mul_f32_e32 v31, 0x3fb8aa3b, v31
	v_mul_f32_e32 v54, 0x3fb8aa3b, v54
	v_mul_f32_e32 v65, 0x3fb8aa3b, v66
	v_mul_f32_e32 v66, 0x3fb8aa3b, v67
	v_mul_f32_e32 v67, 0x3fb8aa3b, v68
	v_mul_f32_e32 v43, 0x3fb8aa3b, v43
	v_mul_f32_e32 v47, 0x3fb8aa3b, v47
	v_mul_f32_e32 v51, 0x3fb8aa3b, v51
	v_mul_f32_e32 v35, 0x3fb8aa3b, v35
	v_exp_f32_e32 v0, v0
	v_exp_f32_e32 v4, v4
	v_exp_f32_e32 v8, v8
	v_exp_f32_e32 v12, v12
	v_exp_f32_e32 v111, v16
	v_exp_f32_e32 v156, v20
	v_exp_f32_e32 v157, v24
	v_exp_f32_e32 v158, v28
	v_exp_f32_e32 v159, v55
	v_exp_f32_e32 v160, v56
	v_exp_f32_e32 v161, v57
	v_exp_f32_e32 v162, v58
	v_exp_f32_e32 v163, v40
	v_exp_f32_e32 v164, v44
	v_exp_f32_e32 v165, v48
	v_exp_f32_e32 v166, v32
	v_exp_f32_e32 v1, v1
	v_exp_f32_e32 v5, v5
	v_exp_f32_e32 v9, v9
	v_exp_f32_e32 v13, v13
	v_exp_f32_e32 v167, v17
	v_exp_f32_e32 v168, v21
	v_exp_f32_e32 v170, v29
	v_exp_f32_e32 v171, v52
	v_exp_f32_e32 v172, v59
	v_exp_f32_e32 v174, v61
	v_exp_f32_e32 v175, v41
	v_exp_f32_e32 v177, v45
	v_exp_f32_e32 v181, v33
	v_exp_f32_e32 v2, v2
	v_exp_f32_e32 v10, v10
	v_exp_f32_e32 v182, v18
	v_exp_f32_e32 v183, v22
	v_exp_f32_e32 v188, v63
	v_exp_f32_e32 v189, v64
	v_exp_f32_e32 v3, v3
	v_exp_f32_e32 v11, v11
	v_lshl_add_u64 v[84:85], v[100:101], 0, v[102:103]
	v_exp_f32_e32 v169, v25
	v_exp_f32_e32 v173, v60
	v_exp_f32_e32 v180, v49
	v_exp_f32_e32 v6, v6
	v_exp_f32_e32 v14, v14
	v_exp_f32_e32 v184, v26
	v_exp_f32_e32 v185, v30
	v_exp_f32_e32 v186, v53
	v_exp_f32_e32 v187, v62
	v_exp_f32_e32 v190, v42
	v_exp_f32_e32 v191, v46
	v_exp_f32_e32 v192, v50
	v_exp_f32_e32 v193, v34
	v_exp_f32_e32 v7, v7
	v_exp_f32_e32 v15, v15
	v_exp_f32_e32 v194, v19
	v_exp_f32_e32 v195, v23
	v_exp_f32_e32 v196, v27
	v_exp_f32_e32 v197, v31
	v_exp_f32_e32 v198, v54
	v_exp_f32_e32 v199, v65
	v_exp_f32_e32 v200, v66
	v_exp_f32_e32 v201, v67
	v_exp_f32_e32 v202, v43
	v_exp_f32_e32 v203, v47
	v_exp_f32_e32 v204, v51
	v_exp_f32_e32 v205, v35
	v_add_co_u32_e32 v36, vcc, s8, v84
	v_add_f32_e32 v16, 0, v0
	s_nop 0
	v_addc_co_u32_e32 v37, vcc, 0, v85, vcc
	v_add_co_u32_e32 v38, vcc, s10, v84
	v_bfe_u32 v17, v0, 16, 1
	v_bfe_u32 v18, v4, 16, 1
	v_bfe_u32 v19, v8, 16, 1
	v_bfe_u32 v20, v12, 16, 1
	v_bfe_u32 v21, v111, 16, 1
	v_bfe_u32 v22, v156, 16, 1
	v_bfe_u32 v23, v157, 16, 1
	v_bfe_u32 v24, v158, 16, 1
	v_bfe_u32 v25, v159, 16, 1
	v_bfe_u32 v26, v160, 16, 1
	v_bfe_u32 v27, v161, 16, 1
	v_bfe_u32 v28, v162, 16, 1
	v_bfe_u32 v29, v163, 16, 1
	v_bfe_u32 v30, v164, 16, 1
	v_bfe_u32 v31, v165, 16, 1
	v_bfe_u32 v32, v166, 16, 1
	v_add_f32_e32 v33, 0, v1
	v_bfe_u32 v34, v1, 16, 1
	v_bfe_u32 v35, v5, 16, 1
	v_bfe_u32 v40, v9, 16, 1
	v_bfe_u32 v41, v13, 16, 1
	v_bfe_u32 v42, v167, 16, 1
	v_bfe_u32 v43, v168, 16, 1
	v_bfe_u32 v45, v170, 16, 1
	v_bfe_u32 v46, v171, 16, 1
	v_bfe_u32 v47, v172, 16, 1
	v_bfe_u32 v49, v174, 16, 1
	v_bfe_u32 v50, v175, 16, 1
	v_bfe_u32 v51, v177, 16, 1
	v_bfe_u32 v53, v181, 16, 1
	v_add_f32_e32 v54, 0, v2
	v_bfe_u32 v55, v2, 16, 1
	v_bfe_u32 v57, v10, 16, 1
	v_bfe_u32 v59, v182, 16, 1
	v_bfe_u32 v60, v183, 16, 1
	v_bfe_u32 v65, v188, 16, 1
	v_bfe_u32 v66, v189, 16, 1
	v_add_f32_e32 v71, 0, v3
	v_bfe_u32 v72, v3, 16, 1
	v_bfe_u32 v74, v11, 16, 1
	v_addc_co_u32_e32 v39, vcc, 0, v85, vcc
	v_bfe_u32 v44, v169, 16, 1
	v_bfe_u32 v48, v173, 16, 1
	v_bfe_u32 v52, v180, 16, 1
	v_bfe_u32 v56, v6, 16, 1
	v_bfe_u32 v58, v14, 16, 1
	v_bfe_u32 v61, v184, 16, 1
	v_bfe_u32 v62, v185, 16, 1
	v_bfe_u32 v63, v186, 16, 1
	v_bfe_u32 v64, v187, 16, 1
	v_bfe_u32 v67, v190, 16, 1
	v_bfe_u32 v68, v191, 16, 1
	v_bfe_u32 v69, v192, 16, 1
	v_bfe_u32 v70, v193, 16, 1
	v_bfe_u32 v73, v7, 16, 1
	v_bfe_u32 v75, v15, 16, 1
	v_bfe_u32 v76, v194, 16, 1
	v_bfe_u32 v77, v195, 16, 1
	v_bfe_u32 v78, v196, 16, 1
	v_bfe_u32 v79, v197, 16, 1
	v_bfe_u32 v80, v198, 16, 1
	v_bfe_u32 v81, v199, 16, 1
	v_bfe_u32 v82, v200, 16, 1
	v_bfe_u32 v83, v201, 16, 1
	v_bfe_u32 v84, v202, 16, 1
	v_bfe_u32 v85, v203, 16, 1
	v_bfe_u32 v86, v204, 16, 1
	v_bfe_u32 v87, v205, 16, 1
	v_add3_u32 v0, v0, v17, s9
	v_add_f32_e32 v16, v4, v16
	v_add3_u32 v4, v4, v18, s9
	v_add3_u32 v17, v8, v19, s9
	v_add3_u32 v18, v12, v20, s9
	v_add3_u32 v19, v111, v21, s9
	v_add3_u32 v20, v156, v22, s9
	v_add3_u32 v21, v157, v23, s9
	v_add3_u32 v22, v158, v24, s9
	v_add3_u32 v23, v159, v25, s9
	v_add3_u32 v24, v160, v26, s9
	v_add3_u32 v25, v161, v27, s9
	v_add3_u32 v26, v162, v28, s9
	v_add3_u32 v27, v163, v29, s9
	v_add3_u32 v28, v164, v30, s9
	v_add3_u32 v29, v165, v31, s9
	v_add3_u32 v30, v166, v32, s9
	v_add3_u32 v1, v1, v34, s9
	v_add_f32_e32 v31, v5, v33
	v_add3_u32 v5, v5, v35, s9
	v_add3_u32 v32, v9, v40, s9
	v_add3_u32 v33, v13, v41, s9
	v_add3_u32 v34, v167, v42, s9
	v_add3_u32 v35, v168, v43, s9
	v_add3_u32 v41, v170, v45, s9
	v_add3_u32 v42, v171, v46, s9
	v_add3_u32 v43, v172, v47, s9
	v_add3_u32 v45, v174, v49, s9
	v_add3_u32 v46, v175, v50, s9
	v_add3_u32 v47, v177, v51, s9
	v_add3_u32 v49, v181, v53, s9
	v_add3_u32 v2, v2, v55, s9
	v_add_f32_e32 v50, v6, v54
	v_add3_u32 v51, v10, v57, s9
	v_add3_u32 v53, v182, v59, s9
	v_add3_u32 v54, v183, v60, s9
	v_add3_u32 v59, v188, v65, s9
	v_add3_u32 v60, v189, v66, s9
	v_add3_u32 v3, v3, v72, s9
	v_add_f32_e32 v65, v7, v71
	v_add3_u32 v66, v11, v74, s9
	v_add3_u32 v40, v169, v44, s9
	v_add3_u32 v44, v173, v48, s9
	v_add3_u32 v48, v180, v52, s9
	v_add3_u32 v6, v6, v56, s9
	v_add3_u32 v52, v14, v58, s9
	v_add3_u32 v55, v184, v61, s9
	v_add3_u32 v56, v185, v62, s9
	v_add3_u32 v57, v186, v63, s9
	v_add3_u32 v58, v187, v64, s9
	v_add3_u32 v61, v190, v67, s9
	v_add3_u32 v62, v191, v68, s9
	v_add3_u32 v63, v192, v69, s9
	v_add3_u32 v64, v193, v70, s9
	v_add3_u32 v7, v7, v73, s9
	v_add3_u32 v67, v15, v75, s9
	v_add3_u32 v68, v194, v76, s9
	v_add3_u32 v69, v195, v77, s9
	v_add3_u32 v70, v196, v78, s9
	v_add3_u32 v71, v197, v79, s9
	v_add3_u32 v72, v198, v80, s9
	v_add3_u32 v73, v199, v81, s9
	v_add3_u32 v74, v200, v82, s9
	v_add3_u32 v75, v201, v83, s9
	v_add3_u32 v76, v202, v84, s9
	v_add3_u32 v77, v203, v85, s9
	v_add3_u32 v78, v204, v86, s9
	v_add3_u32 v79, v205, v87, s9
	ds_write_b16_d16_hi v109, v0
	ds_write_b16_d16_hi v109, v4 offset:32
	v_add_f32_e32 v0, v8, v16
	ds_write_b16_d16_hi v109, v17 offset:64
	ds_write_b16_d16_hi v109, v18 offset:96
	ds_write_b16_d16_hi v109, v19 offset:128
	ds_write_b16_d16_hi v109, v20 offset:160
	ds_write_b16_d16_hi v109, v21 offset:192
	ds_write_b16_d16_hi v109, v22 offset:224
	ds_write_b16_d16_hi v109, v23 offset:256
	ds_write_b16_d16_hi v109, v24 offset:288
	ds_write_b16_d16_hi v109, v25 offset:320
	ds_write_b16_d16_hi v109, v26 offset:352
	ds_write_b16_d16_hi v109, v27 offset:384
	ds_write_b16_d16_hi v109, v28 offset:416
	ds_write_b16_d16_hi v109, v29 offset:448
	ds_write_b16_d16_hi v109, v30 offset:480
	ds_write_b16_d16_hi v109, v1 offset:528
	ds_write_b16_d16_hi v109, v5 offset:560
	v_add_f32_e32 v1, v9, v31
	ds_write_b16_d16_hi v109, v32 offset:592
	ds_write_b16_d16_hi v109, v33 offset:624
	ds_write_b16_d16_hi v109, v34 offset:656
	ds_write_b16_d16_hi v109, v35 offset:688
	ds_write_b16_d16_hi v109, v40 offset:720
	ds_write_b16_d16_hi v109, v41 offset:752
	ds_write_b16_d16_hi v109, v42 offset:784
	ds_write_b16_d16_hi v109, v43 offset:816
	ds_write_b16_d16_hi v109, v44 offset:848
	ds_write_b16_d16_hi v109, v45 offset:880
	ds_write_b16_d16_hi v109, v46 offset:912
	ds_write_b16_d16_hi v109, v47 offset:944
	ds_write_b16_d16_hi v109, v48 offset:976
	ds_write_b16_d16_hi v109, v49 offset:1008
	ds_write_b16_d16_hi v109, v2 offset:1056
	ds_write_b16_d16_hi v109, v6 offset:1088
	v_add_f32_e32 v2, v10, v50
	ds_write_b16_d16_hi v109, v51 offset:1120
	ds_write_b16_d16_hi v109, v52 offset:1152
	ds_write_b16_d16_hi v109, v53 offset:1184
	ds_write_b16_d16_hi v109, v54 offset:1216
	ds_write_b16_d16_hi v109, v55 offset:1248
	ds_write_b16_d16_hi v109, v56 offset:1280
	ds_write_b16_d16_hi v109, v57 offset:1312
	ds_write_b16_d16_hi v109, v58 offset:1344
	ds_write_b16_d16_hi v109, v59 offset:1376
	ds_write_b16_d16_hi v109, v60 offset:1408
	ds_write_b16_d16_hi v109, v61 offset:1440
	ds_write_b16_d16_hi v109, v62 offset:1472
	ds_write_b16_d16_hi v109, v63 offset:1504
	ds_write_b16_d16_hi v109, v64 offset:1536
	ds_write_b16_d16_hi v109, v3 offset:1584
	ds_write_b16_d16_hi v109, v7 offset:1616
	v_add_f32_e32 v3, v11, v65
	ds_write_b16_d16_hi v109, v66 offset:1648
	ds_write_b16_d16_hi v109, v67 offset:1680
	ds_write_b16_d16_hi v109, v68 offset:1712
	ds_write_b16_d16_hi v109, v69 offset:1744
	ds_write_b16_d16_hi v109, v70 offset:1776
	ds_write_b16_d16_hi v109, v71 offset:1808
	ds_write_b16_d16_hi v109, v72 offset:1840
	ds_write_b16_d16_hi v109, v73 offset:1872
	ds_write_b16_d16_hi v109, v74 offset:1904
	ds_write_b16_d16_hi v109, v75 offset:1936
	ds_write_b16_d16_hi v109, v76 offset:1968
	ds_write_b16_d16_hi v109, v77 offset:2000
	ds_write_b16_d16_hi v109, v78 offset:2032
	ds_write_b16_d16_hi v109, v79 offset:2064
	v_add_f32_e32 v206, v12, v0
	v_add_f32_e32 v207, v13, v1
	v_add_f32_e32 v208, v14, v2
	v_add_f32_e32 v209, v15, v3
	ds_read_b128 v[0:3], v104
	ds_read_b128 v[4:7], v104 offset:64
	ds_read_b128 v[8:11], v97 offset:36864
	ds_read_b128 v[12:15], v97 offset:36928
	ds_read_b128 v[16:19], v110 offset:36864
	ds_read_b128 v[20:23], v110 offset:36928
	ds_read_b128 v[24:27], v110 offset:45312
	ds_read_b128 v[28:31], v110 offset:45376
	ds_read_b128 v[32:35], v110 offset:53760
	ds_read_b128 v[40:43], v110 offset:53824
	ds_read_b128 v[44:47], v110 offset:36992
	ds_read_b128 v[48:51], v110 offset:53888
	ds_read_b128 v[52:55], v104 offset:128
	ds_read_b128 v[56:59], v104 offset:192
	ds_read_b128 v[60:63], v97 offset:36992
	ds_read_b128 v[64:67], v97 offset:37056
	s_waitcnt lgkmcnt(13)
	v_mfma_f32_16x16x32_bf16 v[8:11], v[0:3], v[8:11], 0
	ds_read_b128 v[68:71], v110 offset:37056
	ds_read_b128 v[72:75], v110 offset:45440
	ds_read_b128 v[76:79], v110 offset:45504
	ds_read_b128 v[80:83], v110 offset:53952
	ds_read_b128 v[84:87], v104 offset:256
	ds_read_b128 v[88:91], v110 offset:37120
	ds_read_b128 v[92:95], v104 offset:320
	ds_read_b128 v[112:115], v97 offset:37120
	ds_read_b128 v[116:119], v97 offset:37184
	s_waitcnt lgkmcnt(14)
	v_mfma_f32_16x16x32_bf16 v[16:19], v[0:3], v[16:19], 0
	v_cmp_lt_i32_e32 vcc, s11, v96
	v_lshl_add_u64 v[100:101], v[100:101], 0, s[2:3]
	s_or_b64 s[6:7], vcc, s[6:7]
	v_mfma_f32_16x16x32_bf16 v[24:27], v[0:3], v[24:27], 0
	v_mfma_f32_16x16x32_bf16 v[0:3], v[0:3], v[32:35], 0
	ds_read_b128 v[32:35], v110 offset:37184
	ds_read_b128 v[120:123], v110 offset:45568
	ds_read_b128 v[124:127], v110 offset:45632
	v_mfma_f32_16x16x32_bf16 v[8:11], v[4:7], v[12:15], v[8:11]
	ds_read_b128 v[12:15], v110 offset:54016
	ds_read_b128 v[128:131], v110 offset:54080
	ds_read_b128 v[132:135], v97 offset:37248
	v_mfma_f32_16x16x32_bf16 v[16:19], v[4:7], v[20:23], v[16:19]
	ds_read_b128 v[20:23], v110 offset:45696
	ds_read_b128 v[136:139], v104 offset:384
	ds_read_b128 v[140:143], v104 offset:448
	v_mfma_f32_16x16x32_bf16 v[24:27], v[4:7], v[28:31], v[24:27]
	ds_read_b128 v[28:31], v97 offset:37312
	ds_read_b128 v[144:147], v110 offset:37248
	ds_read_b128 v[148:151], v110 offset:37312
	v_mfma_f32_16x16x32_bf16 v[0:3], v[4:7], v[40:43], v[0:3]
	ds_read_b128 v[4:7], v110 offset:45760
	ds_read_b128 v[40:43], v110 offset:54144
	ds_read_b128 v[152:155], v110 offset:54208
	s_nop 0
	s_waitcnt lgkmcnt(14)
	v_mfma_f32_16x16x32_bf16 v[8:11], v[52:55], v[60:63], v[8:11]
	v_add_f32_e32 v60, v111, v206
	v_add_f32_e32 v61, v167, v207
	v_mfma_f32_16x16x32_bf16 v[16:19], v[52:55], v[44:47], v[16:19]
	v_add_f32_e32 v44, v182, v208
	v_add_f32_e32 v45, v194, v209
	v_add_f32_e32 v46, v156, v60
	v_mfma_f32_16x16x32_bf16 v[24:27], v[52:55], v[72:75], v[24:27]
	v_add_f32_e32 v47, v168, v61
	v_add_f32_e32 v44, v183, v44
	v_add_f32_e32 v45, v195, v45
	v_mfma_f32_16x16x32_bf16 v[0:3], v[52:55], v[48:51], v[0:3]
	v_add_f32_e32 v46, v157, v46
	v_add_f32_e32 v47, v169, v47
	v_add_f32_e32 v44, v184, v44
	v_mfma_f32_16x16x32_bf16 v[8:11], v[56:59], v[64:67], v[8:11]
	v_add_f32_e32 v45, v196, v45
	v_add_f32_e32 v46, v158, v46
	v_add_f32_e32 v47, v170, v47
	v_mfma_f32_16x16x32_bf16 v[16:19], v[56:59], v[68:71], v[16:19]
	v_add_f32_e32 v44, v185, v44
	v_add_f32_e32 v45, v197, v45
	v_add_f32_e32 v46, v159, v46
	v_mfma_f32_16x16x32_bf16 v[24:27], v[56:59], v[76:79], v[24:27]
	v_add_f32_e32 v47, v171, v47
	v_add_f32_e32 v44, v186, v44
	v_add_f32_e32 v45, v198, v45
	v_mfma_f32_16x16x32_bf16 v[0:3], v[56:59], v[80:83], v[0:3]
	v_add_f32_e32 v46, v160, v46
	v_add_f32_e32 v47, v172, v47
	v_add_f32_e32 v44, v187, v44
	v_mfma_f32_16x16x32_bf16 v[8:11], v[84:87], v[112:115], v[8:11]
	v_add_f32_e32 v45, v199, v45
	v_add_f32_e32 v46, v161, v46
	v_add_f32_e32 v47, v173, v47
	v_mfma_f32_16x16x32_bf16 v[16:19], v[84:87], v[88:91], v[16:19]
	v_add_f32_e32 v44, v188, v44
	v_add_f32_e32 v45, v200, v45
	v_add_f32_e32 v46, v162, v46
	s_waitcnt lgkmcnt(13)
	v_mfma_f32_16x16x32_bf16 v[24:27], v[84:87], v[120:123], v[24:27]
	v_add_f32_e32 v47, v174, v47
	v_add_f32_e32 v44, v189, v44
	v_add_f32_e32 v45, v201, v45
	s_waitcnt lgkmcnt(11)
	v_mfma_f32_16x16x32_bf16 v[0:3], v[84:87], v[12:15], v[0:3]
	v_add_f32_e32 v12, v163, v46
	v_add_f32_e32 v13, v175, v47
	v_add_f32_e32 v44, v190, v44
	v_mfma_f32_16x16x32_bf16 v[8:11], v[92:95], v[116:119], v[8:11]
	v_add_f32_e32 v45, v202, v45
	v_add_f32_e32 v46, v164, v12
	v_add_f32_e32 v47, v177, v13
	v_mfma_f32_16x16x32_bf16 v[12:15], v[92:95], v[32:35], v[16:19]
	v_add_f32_e32 v32, v191, v44
	v_add_f32_e32 v33, v203, v45
	v_add_f32_e32 v34, v165, v46
	v_mfma_f32_16x16x32_bf16 v[16:19], v[92:95], v[124:127], v[24:27]
	s_waitcnt lgkmcnt(10)
	v_mfma_f32_16x16x32_bf16 v[0:3], v[92:95], v[128:131], v[0:3]
	s_nop 0
	v_add_f32_e32 v24, v180, v47
	v_add_f32_e32 v25, v192, v32
	v_add_f32_e32 v26, v204, v33
	v_add_f32_e32 v27, v166, v34
	v_add_f32_e32 v24, v181, v24
	v_add_f32_e32 v25, v193, v25
	s_waitcnt lgkmcnt(7)
	v_mfma_f32_16x16x32_bf16 v[8:11], v[136:139], v[132:135], v[8:11]
	v_add_f32_e32 v26, v205, v26
	v_add_f32_dpp v27, v27, v27 row_ror:8 row_mask:0xf bank_mask:0xf bound_ctrl:1
	v_add_f32_dpp v24, v24, v24 row_ror:8 row_mask:0xf bank_mask:0xf bound_ctrl:1
	s_waitcnt lgkmcnt(4)
	v_mfma_f32_16x16x32_bf16 v[12:15], v[136:139], v[144:147], v[12:15]
	v_add_f32_dpp v25, v25, v25 row_ror:8 row_mask:0xf bank_mask:0xf bound_ctrl:1
	v_add_f32_dpp v26, v26, v26 row_ror:8 row_mask:0xf bank_mask:0xf bound_ctrl:1
	v_add_f32_dpp v27, v27, v27 row_ror:4 row_mask:0xf bank_mask:0xf bound_ctrl:1
	v_mfma_f32_16x16x32_bf16 v[16:19], v[136:139], v[20:23], v[16:19]
	v_add_f32_dpp v20, v24, v24 row_ror:4 row_mask:0xf bank_mask:0xf bound_ctrl:1
	v_add_f32_dpp v21, v25, v25 row_ror:4 row_mask:0xf bank_mask:0xf bound_ctrl:1
	v_add_f32_dpp v22, v26, v26 row_ror:4 row_mask:0xf bank_mask:0xf bound_ctrl:1
	s_waitcnt lgkmcnt(1)
	v_mfma_f32_16x16x32_bf16 v[0:3], v[136:139], v[40:43], v[0:3]
	v_add_f32_dpp v23, v27, v27 row_ror:2 row_mask:0xf bank_mask:0xf bound_ctrl:1
	v_add_f32_dpp v20, v20, v20 row_ror:2 row_mask:0xf bank_mask:0xf bound_ctrl:1
	v_add_f32_dpp v21, v21, v21 row_ror:2 row_mask:0xf bank_mask:0xf bound_ctrl:1
	v_add_f32_dpp v22, v22, v22 row_ror:2 row_mask:0xf bank_mask:0xf bound_ctrl:1
	v_add_f32_dpp v23, v23, v23 row_ror:1 row_mask:0xf bank_mask:0xf bound_ctrl:1
	v_mfma_f32_16x16x32_bf16 v[8:11], v[140:143], v[28:31], v[8:11]
	v_add_f32_dpp v20, v20, v20 row_ror:1 row_mask:0xf bank_mask:0xf bound_ctrl:1
	v_add_f32_dpp v21, v21, v21 row_ror:1 row_mask:0xf bank_mask:0xf bound_ctrl:1
	v_add_f32_dpp v22, v22, v22 row_ror:1 row_mask:0xf bank_mask:0xf bound_ctrl:1
	v_rcp_f32_e32 v23, v23
	v_mfma_f32_16x16x32_bf16 v[12:15], v[140:143], v[148:151], v[12:15]
	s_nop 2
	v_mul_f32_e32 v8, v23, v8
	v_mfma_f32_16x16x32_bf16 v[4:7], v[140:143], v[4:7], v[16:19]
	s_nop 2
	v_rcp_f32_e32 v16, v20
	v_rcp_f32_e32 v17, v21
	v_rcp_f32_e32 v18, v22
	s_waitcnt lgkmcnt(0)
	v_mfma_f32_16x16x32_bf16 v[0:3], v[140:143], v[152:155], v[0:3]
	v_mul_f32_e32 v9, v16, v9
	v_mul_f32_e32 v10, v17, v10
	v_mul_f32_e32 v11, v18, v11
	v_mul_f32_e32 v12, v23, v12
	v_mul_f32_e32 v13, v16, v13
	v_mul_f32_e32 v14, v17, v14
	v_mul_f32_e32 v15, v18, v15
	v_mul_f32_e32 v4, v23, v4
	v_mul_f32_e32 v5, v16, v5
	v_mul_f32_e32 v6, v17, v6
	v_mul_f32_e32 v7, v18, v7
	v_mul_f32_e32 v0, v23, v0
	v_mul_f32_e32 v1, v16, v1
	v_mul_f32_e32 v2, v17, v2
	v_mul_f32_e32 v3, v18, v3
	v_bfe_u32 v16, v8, 16, 1
	v_bfe_u32 v17, v9, 16, 1
	v_bfe_u32 v18, v10, 16, 1
	v_bfe_u32 v19, v11, 16, 1
	v_bfe_u32 v20, v12, 16, 1
	v_bfe_u32 v21, v13, 16, 1
	v_bfe_u32 v22, v14, 16, 1
	v_bfe_u32 v23, v15, 16, 1
	v_bfe_u32 v24, v4, 16, 1
	v_bfe_u32 v25, v5, 16, 1
	v_bfe_u32 v26, v6, 16, 1
	v_bfe_u32 v27, v7, 16, 1
	v_bfe_u32 v28, v0, 16, 1
	v_bfe_u32 v29, v1, 16, 1
	v_bfe_u32 v30, v2, 16, 1
	v_bfe_u32 v31, v3, 16, 1
	v_add3_u32 v8, v8, v16, s9
	v_add3_u32 v9, v9, v17, s9
	v_add3_u32 v10, v10, v18, s9
	v_add3_u32 v11, v11, v19, s9
	v_add3_u32 v12, v12, v20, s9
	v_add3_u32 v13, v13, v21, s9
	v_add3_u32 v14, v14, v22, s9
	v_add3_u32 v15, v15, v23, s9
	v_add3_u32 v4, v4, v24, s9
	v_add3_u32 v5, v5, v25, s9
	v_add3_u32 v6, v6, v26, s9
	v_add3_u32 v7, v7, v27, s9
	v_add3_u32 v0, v0, v28, s9
	v_add3_u32 v1, v1, v29, s9
	v_add3_u32 v2, v2, v30, s9
	v_add3_u32 v3, v3, v31, s9
	s_andn2_b64 vcc, exec, s[6:7]
	s_cbranch_vccz .Lma_nopf_a
	v_lshl_add_u64 v[240:241], v[100:101], 0, v[98:99]
	v_add_co_u32_e32 v240, vcc, 0x1b400000, v240
	s_nop 1
	v_addc_co_u32_e32 v241, vcc, 0, v241, vcc
	global_load_dwordx4 v[232:235], v[240:241], off offset:1536
	global_load_dwordx4 v[236:239], v[240:241], off offset:1600
.Lma_nopf_a:
	global_store_short_d16_hi v[36:37], v8, off offset:1536
	global_store_short_d16_hi v[36:37], v9, off offset:3584
	global_store_short_d16_hi v[38:39], v10, off offset:1536
	global_store_short_d16_hi v[38:39], v11, off offset:3584
	global_store_short_d16_hi v[36:37], v12, off offset:1568
	global_store_short_d16_hi v[36:37], v13, off offset:3616
	global_store_short_d16_hi v[38:39], v14, off offset:1568
	global_store_short_d16_hi v[38:39], v15, off offset:3616
	global_store_short_d16_hi v[36:37], v4, off offset:1600
	global_store_short_d16_hi v[36:37], v5, off offset:3648
	global_store_short_d16_hi v[38:39], v6, off offset:1600
	global_store_short_d16_hi v[38:39], v7, off offset:3648
	global_store_short_d16_hi v[36:37], v0, off offset:1632
	global_store_short_d16_hi v[36:37], v1, off offset:3680
	global_store_short_d16_hi v[38:39], v2, off offset:1632
	global_store_short_d16_hi v[38:39], v3, off offset:3680
	s_andn2_b64 exec, exec, s[6:7]
	s_cbranch_execnz .LBB0_643

.LBB0_2090:
	global_load_dwordx4 v[120:123], v[0:1], off
	v_lshl_add_u64 v[0:1], v[0:1], 0, s[8:9]
	global_load_dwordx4 v[124:127], v[0:1], off
	v_lshl_add_u64 v[0:1], v[0:1], 0, s[8:9]
	global_load_dwordx4 v[128:131], v[0:1], off
	v_lshl_add_u64 v[0:1], v[0:1], 0, s[8:9]
	global_load_dwordx4 v[132:135], v[0:1], off
	v_lshl_add_u64 v[0:1], v[0:1], 0, s[8:9]
	v_mov_b32_e32 v136, v2
	v_add_u32_e32 v2, 0x8400, v2
	s_waitcnt vmcnt(0)
	ds_write_b128 v116, v[100:103]
	ds_write_b128 v116, v[104:107] offset:9216
	ds_write_b128 v116, v[108:111] offset:18432
	ds_write_b128 v116, v[112:115] offset:27648
	ds_write_b128 v136, v[120:123]
	ds_write_b128 v136, v[124:127] offset:8448
	ds_write_b128 v136, v[128:131] offset:16896
	ds_write_b128 v136, v[132:135] offset:25344
	s_or_b64 exec, exec, s[6:7]
	s_and_b32 s5, s90, -8
	v_add_u32_e32 v96, s5, v179
	s_movk_i32 s5, 0x400
	v_cmp_gt_i32_e32 vcc, s5, v96
	s_waitcnt lgkmcnt(0)
	s_barrier
	s_and_saveexec_b64 s[6:7], vcc
	s_cbranch_execz .LBB0_2094
	s_lshl_b32 s8, s90, 23
	s_and_b32 s8, s8, 0x2000000
	v_bfe_u32 v2, v176, 4, 2
	v_and_b32_e32 v0, 15, v176
	s_movk_i32 s5, 0x2100
	v_mov_b32_e32 v1, 0x11400
	s_add_u32 s2, s2, s10
	v_mad_u32_u24 v1, v179, s5, v1
	v_lshlrev_b32_e32 v3, 1, v0
	v_mul_u32_u24_e32 v5, 0x210, v0
	v_lshlrev_b32_e32 v6, 4, v2
	s_movk_i32 s5, 0x90
	v_mov_b32_e32 v99, 0
	s_addc_u32 s3, s3, 0
	v_or_b32_e32 v4, v1, v3
	v_add3_u32 v104, v1, v5, v6
	v_mad_u32_u24 v105, v0, s5, v6
	v_or_b32_e32 v1, 16, v0
	s_movk_i32 s5, 0x840
	v_mov_b32_e32 v97, v99
	s_add_u32 s2, s2, s8
	v_mad_u32_u24 v109, v2, s5, v4
	v_mul_u32_u24_e32 v4, 0x210, v1
	v_lshl_or_b32 v98, v0, 11, v6
	s_mov_b32 s5, 0
	v_lshlrev_b64 v[0:1], 15, v[96:97]
	s_addc_u32 s3, s3, 0
	v_add_u32_e32 v106, 0x900, v105
	v_add_u32_e32 v107, 0x1200, v105
	v_add_u32_e32 v108, 0x1b00, v105
	v_lshl_add_u64 v[100:101], s[2:3], 0, v[0:1]
	s_lshl_b64 s[2:3], s[4:5], 15
	v_lshl_or_b32 v102, v2, 13, v3
	v_mov_b32_e32 v103, v99
	s_mov_b64 s[8:9], 0
	s_mov_b32 s5, 0x1b400000
	s_movk_i32 s10, 0x7fff
	v_add_u32_e32 v97, v6, v5
	v_add_u32_e32 v110, v6, v4
	s_mov_b32 s11, 0x1b401000
	s_movk_i32 s12, 0x3ff
	v_lshl_add_u64 v[240:241], v[100:101], 0, v[98:99]
	v_add_co_u32_e32 v240, vcc, 0x1b400000, v240
	s_nop 1
	v_addc_co_u32_e32 v241, vcc, 0, v241, vcc
	global_load_dwordx4 v[232:235], v[240:241], off offset:1536
	global_load_dwordx4 v[236:239], v[240:241], off offset:1600
	s_waitcnt vmcnt(0)
.LBB0_2093:
	ds_read_b128 v[0:3], v105
	ds_read_b128 v[4:7], v105 offset:64
	ds_read_b128 v[12:15], v106
	ds_read_b128 v[16:19], v106 offset:64
	ds_read_b128 v[20:23], v107
	ds_read_b128 v[24:27], v107 offset:64
	ds_read_b128 v[28:31], v108
	ds_read_b128 v[68:71], v108 offset:64
	ds_read_b128 v[36:39], v105 offset:9216
	ds_read_b128 v[112:115], v105 offset:9280
	v_mov_b32_e32 v111, 0
	v_add_u32_e32 v96, s4, v96
	s_waitcnt vmcnt(16) lgkmcnt(0)
	v_mov_b32_e32 v8, v232
	v_mov_b32_e32 v9, v233
	v_mov_b32_e32 v10, v234
	v_mov_b32_e32 v11, v235
	v_mov_b32_e32 v32, v236
	v_mov_b32_e32 v33, v237
	v_mov_b32_e32 v34, v238
	v_mov_b32_e32 v35, v239
	s_nop 1
	v_mfma_f32_16x16x32_bf16 v[116:119], v[8:11], v[36:39], 0
	ds_read_b128 v[36:39], v105 offset:11520
	ds_read_b128 v[120:123], v105 offset:11584
	s_waitcnt lgkmcnt(1)
	v_mfma_f32_16x16x32_bf16 v[124:127], v[8:11], v[36:39], 0
	ds_read_b128 v[36:39], v105 offset:13824
	ds_read_b128 v[128:131], v105 offset:13888
	s_waitcnt lgkmcnt(1)
	v_mfma_f32_16x16x32_bf16 v[132:135], v[8:11], v[36:39], 0
	ds_read_b128 v[36:39], v105 offset:16128
	ds_read_b128 v[136:139], v105 offset:16192
	s_waitcnt lgkmcnt(1)
	v_mfma_f32_16x16x32_bf16 v[140:143], v[8:11], v[36:39], 0
	ds_read_b128 v[36:39], v105 offset:18432
	ds_read_b128 v[144:147], v105 offset:18496
	s_waitcnt lgkmcnt(1)
	v_mfma_f32_16x16x32_bf16 v[148:151], v[8:11], v[36:39], 0
	ds_read_b128 v[36:39], v105 offset:20736
	ds_read_b128 v[72:75], v105 offset:20800
	s_waitcnt lgkmcnt(1)
	v_mfma_f32_16x16x32_bf16 v[92:95], v[8:11], v[36:39], 0
	ds_read_b128 v[36:39], v105 offset:23040
	ds_read_b128 v[76:79], v105 offset:23104
	s_waitcnt lgkmcnt(1)
	v_mfma_f32_16x16x32_bf16 v[88:91], v[8:11], v[36:39], 0
	ds_read_b128 v[36:39], v105 offset:25344
	ds_read_b128 v[80:83], v105 offset:25408
	v_mfma_f32_16x16x32_bf16 v[0:3], v[8:11], v[0:3], 0
	v_mfma_f32_16x16x32_bf16 v[12:15], v[8:11], v[12:15], 0
	s_waitcnt lgkmcnt(1)
	v_mfma_f32_16x16x32_bf16 v[84:87], v[8:11], v[36:39], 0
	ds_read_b128 v[40:43], v105 offset:27648
	ds_read_b128 v[36:39], v105 offset:27712
	ds_read_b128 v[48:51], v105 offset:29952
	ds_read_b128 v[44:47], v105 offset:30016
	ds_read_b128 v[56:59], v105 offset:32256
	ds_read_b128 v[52:55], v105 offset:32320
	v_mfma_f32_16x16x32_bf16 v[20:23], v[8:11], v[20:23], 0
	ds_read_b128 v[64:67], v105 offset:34560
	ds_read_b128 v[60:63], v105 offset:34624
	v_mfma_f32_16x16x32_bf16 v[28:31], v[8:11], v[28:31], 0
	s_waitcnt lgkmcnt(5)
	v_mfma_f32_16x16x32_bf16 v[48:51], v[8:11], v[48:51], 0
	s_waitcnt lgkmcnt(3)
	v_mfma_f32_16x16x32_bf16 v[56:59], v[8:11], v[56:59], 0
	v_mfma_f32_16x16x32_bf16 v[0:3], v[32:35], v[4:7], v[0:3]
	v_mfma_f32_16x16x32_bf16 v[4:7], v[32:35], v[16:19], v[12:15]
	v_mfma_f32_16x16x32_bf16 v[40:43], v[8:11], v[40:43], 0
	s_waitcnt lgkmcnt(1)
	v_mfma_f32_16x16x32_bf16 v[64:67], v[8:11], v[64:67], 0
	v_mfma_f32_16x16x32_bf16 v[8:11], v[32:35], v[24:27], v[20:23]
	v_mfma_f32_16x16x32_bf16 v[12:15], v[32:35], v[68:71], v[28:31]
	v_mfma_f32_16x16x32_bf16 v[16:19], v[32:35], v[112:115], v[116:119]
	v_mov_b32_e32 v114, 0
	v_mov_b32_e32 v113, 0
	v_mov_b32_e32 v112, 0
	v_mfma_f32_16x16x32_bf16 v[20:23], v[32:35], v[120:123], v[124:127]
	v_mov_b32_e32 v118, 0
	v_mov_b32_e32 v119, 0
	v_mov_b32_e32 v117, 0
	v_mfma_f32_16x16x32_bf16 v[24:27], v[32:35], v[128:131], v[132:135]
	v_mov_b32_e32 v116, 0
	v_mov_b32_e32 v115, 0
	v_mfma_f32_16x16x32_bf16 v[28:31], v[32:35], v[136:139], v[140:143]
	v_mfma_f32_16x16x32_bf16 v[44:47], v[32:35], v[44:47], v[48:51]
	v_mfma_f32_16x16x32_bf16 v[48:51], v[32:35], v[52:55], v[56:59]
	v_max_f32_e32 v52, v4, v4
	v_max_f32_e32 v53, v0, v0
	v_max_f32_e32 v54, v5, v5
	v_max_f32_e32 v55, v1, v1
	v_max_f32_e32 v56, v6, v6
	v_max_f32_e32 v57, v2, v2
	v_max_f32_e32 v58, v7, v7
	v_max_f32_e32 v59, v3, v3
	v_mfma_f32_16x16x32_bf16 v[68:71], v[32:35], v[144:147], v[148:151]
	v_max_f32_e32 v52, v53, v52
	v_max_f32_e32 v53, v55, v54
	v_max_f32_e32 v54, v57, v56
	v_mfma_f32_16x16x32_bf16 v[72:75], v[32:35], v[72:75], v[92:95]
	v_max_f32_e32 v55, v59, v58
	v_max3_f32 v52, v52, v8, v12
	v_max3_f32 v53, v53, v9, v13
	v_mfma_f32_16x16x32_bf16 v[76:79], v[32:35], v[76:79], v[88:91]
	v_max3_f32 v54, v54, v10, v14
	v_max3_f32 v55, v55, v11, v15
	v_max3_f32 v52, v52, v16, v20
	v_mfma_f32_16x16x32_bf16 v[80:83], v[32:35], v[80:83], v[84:87]
	v_max3_f32 v53, v53, v17, v21
	v_max3_f32 v54, v54, v18, v22
	v_max3_f32 v55, v55, v19, v23
	v_mfma_f32_16x16x32_bf16 v[40:43], v[32:35], v[36:39], v[40:43]
	v_max3_f32 v52, v52, v24, v28
	v_max3_f32 v53, v53, v25, v29
	v_max3_f32 v54, v54, v26, v30
	s_waitcnt lgkmcnt(0)
	v_mfma_f32_16x16x32_bf16 v[32:35], v[32:35], v[60:63], v[64:67]
	v_max3_f32 v55, v55, v27, v31
	v_max3_f32 v52, v52, v68, v72
	v_max3_f32 v53, v53, v69, v73
	v_max3_f32 v54, v54, v70, v74
	v_max3_f32 v55, v55, v71, v75
	v_max3_f32 v52, v52, v76, v80
	v_max3_f32 v53, v53, v77, v81
	v_max3_f32 v54, v54, v78, v82
	v_max3_f32 v55, v55, v79, v83
	v_max3_f32 v52, v52, v40, v44
	v_max3_f32 v53, v53, v41, v45
	v_max3_f32 v54, v54, v42, v46
	v_max3_f32 v55, v55, v43, v47
	v_mov_b32_e32 v88, 0
	v_max3_f32 v52, v52, v48, v32
	v_max3_f32 v53, v53, v49, v33
	v_max3_f32 v54, v54, v50, v34
	v_max3_f32 v55, v55, v51, v35
	v_mov_b32_dpp v114, v52 row_ror:8 row_mask:0xf bank_mask:0xf
	v_mov_b32_dpp v118, v53 row_ror:8 row_mask:0xf bank_mask:0xf
	v_mov_b32_dpp v119, v54 row_ror:8 row_mask:0xf bank_mask:0xf
	v_mov_b32_dpp v88, v55 row_ror:8 row_mask:0xf bank_mask:0xf
	v_max_f32_e32 v56, v114, v114
	v_max_f32_e32 v57, v118, v118
	v_max_f32_e32 v58, v119, v119
	v_max_f32_e32 v59, v88, v88
	v_mov_b32_e32 v92, 0
	v_mov_b32_e32 v89, 0
	v_max_f32_e32 v52, v52, v56
	v_max_f32_e32 v53, v53, v57
	v_max_f32_e32 v54, v54, v58
	v_max_f32_e32 v55, v55, v59
	v_mov_b32_dpp v113, v52 row_ror:4 row_mask:0xf bank_mask:0xf
	v_mov_b32_dpp v117, v53 row_ror:4 row_mask:0xf bank_mask:0xf
	v_mov_b32_dpp v92, v54 row_ror:4 row_mask:0xf bank_mask:0xf
	v_mov_b32_dpp v89, v55 row_ror:4 row_mask:0xf bank_mask:0xf
	v_max_f32_e32 v56, v113, v113
	v_max_f32_e32 v57, v117, v117
	v_max_f32_e32 v58, v92, v92
	v_max_f32_e32 v59, v89, v89
	v_mov_b32_e32 v93, 0
	v_mov_b32_e32 v90, 0
	v_max_f32_e32 v52, v52, v56
	v_max_f32_e32 v53, v53, v57
	v_max_f32_e32 v54, v54, v58
	v_max_f32_e32 v55, v55, v59
	v_mov_b32_dpp v112, v52 row_ror:2 row_mask:0xf bank_mask:0xf
	v_mov_b32_dpp v116, v53 row_ror:2 row_mask:0xf bank_mask:0xf
	v_mov_b32_dpp v93, v54 row_ror:2 row_mask:0xf bank_mask:0xf
	v_mov_b32_dpp v90, v55 row_ror:2 row_mask:0xf bank_mask:0xf
	v_max_f32_e32 v56, v112, v112
	v_max_f32_e32 v57, v116, v116
	v_max_f32_e32 v58, v93, v93
	v_max_f32_e32 v59, v90, v90
	v_mov_b32_e32 v94, 0
	v_mov_b32_e32 v86, 0
	v_max_f32_e32 v52, v52, v56
	v_max_f32_e32 v53, v53, v57
	v_max_f32_e32 v54, v54, v58
	v_max_f32_e32 v55, v55, v59
	v_mov_b32_dpp v111, v52 row_ror:1 row_mask:0xf bank_mask:0xf
	v_mov_b32_dpp v115, v53 row_ror:1 row_mask:0xf bank_mask:0xf
	v_mov_b32_dpp v94, v54 row_ror:1 row_mask:0xf bank_mask:0xf
	v_mov_b32_dpp v86, v55 row_ror:1 row_mask:0xf bank_mask:0xf
	v_max_f32_e32 v56, v111, v111
	v_max_f32_e32 v57, v115, v115
	v_max_f32_e32 v58, v94, v94
	v_max_f32_e32 v59, v86, v86
	v_max_f32_e32 v52, v52, v56
	v_max_f32_e32 v53, v53, v57
	v_max_f32_e32 v54, v54, v58
	v_max_f32_e32 v55, v55, v59
	v_sub_f32_e32 v0, v0, v52
	v_sub_f32_e32 v4, v4, v52
	v_sub_f32_e32 v8, v8, v52
	v_sub_f32_e32 v12, v12, v52
	v_sub_f32_e32 v16, v16, v52
	v_sub_f32_e32 v20, v20, v52
	v_sub_f32_e32 v24, v24, v52
	v_sub_f32_e32 v28, v28, v52
	v_sub_f32_e32 v56, v68, v52
	v_sub_f32_e32 v57, v72, v52
	v_sub_f32_e32 v58, v76, v52
	v_sub_f32_e32 v59, v80, v52
	v_sub_f32_e32 v40, v40, v52
	v_sub_f32_e32 v44, v44, v52
	v_sub_f32_e32 v48, v48, v52
	v_sub_f32_e32 v32, v32, v52
	v_sub_f32_e32 v1, v1, v53
	v_sub_f32_e32 v5, v5, v53
	v_sub_f32_e32 v9, v9, v53
	v_sub_f32_e32 v13, v13, v53
	v_sub_f32_e32 v17, v17, v53
	v_sub_f32_e32 v21, v21, v53
	v_sub_f32_e32 v29, v29, v53
	v_sub_f32_e32 v52, v69, v53
	v_sub_f32_e32 v60, v73, v53
	v_sub_f32_e32 v61, v77, v53
	v_sub_f32_e32 v62, v81, v53
	v_sub_f32_e32 v41, v41, v53
	v_sub_f32_e32 v45, v45, v53
	v_sub_f32_e32 v33, v33, v53
	v_sub_f32_e32 v2, v2, v54
	v_sub_f32_e32 v10, v10, v54
	v_sub_f32_e32 v18, v18, v54
	v_sub_f32_e32 v22, v22, v54
	v_sub_f32_e32 v63, v74, v54
	v_sub_f32_e32 v64, v78, v54
	v_sub_f32_e32 v65, v82, v54
	v_sub_f32_e32 v3, v3, v55
	v_sub_f32_e32 v11, v11, v55
	v_sub_f32_e32 v25, v25, v53
	v_sub_f32_e32 v49, v49, v53
	v_sub_f32_e32 v6, v6, v54
	v_sub_f32_e32 v14, v14, v54
	v_sub_f32_e32 v26, v26, v54
	v_sub_f32_e32 v30, v30, v54
	v_sub_f32_e32 v53, v70, v54
	v_sub_f32_e32 v42, v42, v54
	v_sub_f32_e32 v46, v46, v54
	v_sub_f32_e32 v50, v50, v54
	v_sub_f32_e32 v34, v34, v54
	v_sub_f32_e32 v7, v7, v55
	v_sub_f32_e32 v15, v15, v55
	v_sub_f32_e32 v19, v19, v55
	v_sub_f32_e32 v23, v23, v55
	v_sub_f32_e32 v27, v27, v55
	v_sub_f32_e32 v31, v31, v55
	v_sub_f32_e32 v54, v71, v55
	v_sub_f32_e32 v66, v75, v55
	v_sub_f32_e32 v67, v79, v55
	v_sub_f32_e32 v68, v83, v55
	v_sub_f32_e32 v43, v43, v55
	v_sub_f32_e32 v47, v47, v55
	v_sub_f32_e32 v51, v51, v55
	v_sub_f32_e32 v35, v35, v55
	v_mul_f32_e32 v0, 0x3fb8aa3b, v0
	v_mul_f32_e32 v4, 0x3fb8aa3b, v4
	v_mul_f32_e32 v8, 0x3fb8aa3b, v8
	v_mul_f32_e32 v12, 0x3fb8aa3b, v12
	v_mul_f32_e32 v16, 0x3fb8aa3b, v16
	v_mul_f32_e32 v20, 0x3fb8aa3b, v20
	v_mul_f32_e32 v24, 0x3fb8aa3b, v24
	v_mul_f32_e32 v28, 0x3fb8aa3b, v28
	v_mul_f32_e32 v55, 0x3fb8aa3b, v56
	v_mul_f32_e32 v56, 0x3fb8aa3b, v57
	v_mul_f32_e32 v57, 0x3fb8aa3b, v58
	v_mul_f32_e32 v58, 0x3fb8aa3b, v59
	v_mul_f32_e32 v40, 0x3fb8aa3b, v40
	v_mul_f32_e32 v44, 0x3fb8aa3b, v44
	v_mul_f32_e32 v48, 0x3fb8aa3b, v48
	v_mul_f32_e32 v32, 0x3fb8aa3b, v32
	v_mul_f32_e32 v1, 0x3fb8aa3b, v1
	v_mul_f32_e32 v5, 0x3fb8aa3b, v5
	v_mul_f32_e32 v9, 0x3fb8aa3b, v9
	v_mul_f32_e32 v13, 0x3fb8aa3b, v13
	v_mul_f32_e32 v17, 0x3fb8aa3b, v17
	v_mul_f32_e32 v21, 0x3fb8aa3b, v21
	v_mul_f32_e32 v29, 0x3fb8aa3b, v29
	v_mul_f32_e32 v52, 0x3fb8aa3b, v52
	v_mul_f32_e32 v59, 0x3fb8aa3b, v60
	v_mul_f32_e32 v60, 0x3fb8aa3b, v61
	v_mul_f32_e32 v61, 0x3fb8aa3b, v62
	v_mul_f32_e32 v41, 0x3fb8aa3b, v41
	v_mul_f32_e32 v45, 0x3fb8aa3b, v45
	v_mul_f32_e32 v33, 0x3fb8aa3b, v33
	v_mul_f32_e32 v2, 0x3fb8aa3b, v2
	v_mul_f32_e32 v10, 0x3fb8aa3b, v10
	v_mul_f32_e32 v18, 0x3fb8aa3b, v18
	v_mul_f32_e32 v22, 0x3fb8aa3b, v22
	v_mul_f32_e32 v62, 0x3fb8aa3b, v63
	v_mul_f32_e32 v63, 0x3fb8aa3b, v64
	v_mul_f32_e32 v64, 0x3fb8aa3b, v65
	v_mul_f32_e32 v3, 0x3fb8aa3b, v3
	v_mul_f32_e32 v11, 0x3fb8aa3b, v11
	v_mul_f32_e32 v25, 0x3fb8aa3b, v25
	v_mul_f32_e32 v49, 0x3fb8aa3b, v49
	v_mul_f32_e32 v6, 0x3fb8aa3b, v6
	v_mul_f32_e32 v14, 0x3fb8aa3b, v14
	v_mul_f32_e32 v26, 0x3fb8aa3b, v26
	v_mul_f32_e32 v30, 0x3fb8aa3b, v30
	v_mul_f32_e32 v53, 0x3fb8aa3b, v53
	v_mul_f32_e32 v42, 0x3fb8aa3b, v42
	v_mul_f32_e32 v46, 0x3fb8aa3b, v46
	v_mul_f32_e32 v50, 0x3fb8aa3b, v50
	v_mul_f32_e32 v34, 0x3fb8aa3b, v34
	v_mul_f32_e32 v7, 0x3fb8aa3b, v7
	v_mul_f32_e32 v15, 0x3fb8aa3b, v15
	v_mul_f32_e32 v19, 0x3fb8aa3b, v19
	v_mul_f32_e32 v23, 0x3fb8aa3b, v23
	v_mul_f32_e32 v27, 0x3fb8aa3b, v27
	v_mul_f32_e32 v31, 0x3fb8aa3b, v31
	v_mul_f32_e32 v54, 0x3fb8aa3b, v54
	v_mul_f32_e32 v65, 0x3fb8aa3b, v66
	v_mul_f32_e32 v66, 0x3fb8aa3b, v67
	v_mul_f32_e32 v67, 0x3fb8aa3b, v68
	v_mul_f32_e32 v43, 0x3fb8aa3b, v43
	v_mul_f32_e32 v47, 0x3fb8aa3b, v47
	v_mul_f32_e32 v51, 0x3fb8aa3b, v51
	v_mul_f32_e32 v35, 0x3fb8aa3b, v35
	v_exp_f32_e32 v0, v0
	v_exp_f32_e32 v4, v4
	v_exp_f32_e32 v8, v8
	v_exp_f32_e32 v12, v12
	v_exp_f32_e32 v111, v16
	v_exp_f32_e32 v156, v20
	v_exp_f32_e32 v157, v24
	v_exp_f32_e32 v158, v28
	v_exp_f32_e32 v159, v55
	v_exp_f32_e32 v160, v56
	v_exp_f32_e32 v161, v57
	v_exp_f32_e32 v162, v58
	v_exp_f32_e32 v163, v40
	v_exp_f32_e32 v164, v44
	v_exp_f32_e32 v165, v48
	v_exp_f32_e32 v166, v32
	v_exp_f32_e32 v1, v1
	v_exp_f32_e32 v5, v5
	v_exp_f32_e32 v9, v9
	v_exp_f32_e32 v13, v13
	v_exp_f32_e32 v167, v17
	v_exp_f32_e32 v168, v21
	v_exp_f32_e32 v170, v29
	v_exp_f32_e32 v171, v52
	v_exp_f32_e32 v172, v59
	v_exp_f32_e32 v174, v61
	v_exp_f32_e32 v175, v41
	v_exp_f32_e32 v177, v45
	v_exp_f32_e32 v179, v33
	v_exp_f32_e32 v2, v2
	v_exp_f32_e32 v10, v10
	v_exp_f32_e32 v180, v18
	v_exp_f32_e32 v181, v22
	v_exp_f32_e32 v186, v63
	v_exp_f32_e32 v187, v64
	v_exp_f32_e32 v3, v3
	v_exp_f32_e32 v11, v11
	v_lshl_add_u64 v[84:85], v[100:101], 0, v[102:103]
	v_exp_f32_e32 v169, v25
	v_exp_f32_e32 v173, v60
	v_exp_f32_e32 v178, v49
	v_exp_f32_e32 v6, v6
	v_exp_f32_e32 v14, v14
	v_exp_f32_e32 v182, v26
	v_exp_f32_e32 v183, v30
	v_exp_f32_e32 v184, v53
	v_exp_f32_e32 v185, v62
	v_exp_f32_e32 v188, v42
	v_exp_f32_e32 v189, v46
	v_exp_f32_e32 v190, v50
	v_exp_f32_e32 v191, v34
	v_exp_f32_e32 v7, v7
	v_exp_f32_e32 v15, v15
	v_exp_f32_e32 v192, v19
	v_exp_f32_e32 v193, v23
	v_exp_f32_e32 v194, v27
	v_exp_f32_e32 v195, v31
	v_exp_f32_e32 v196, v54
	v_exp_f32_e32 v197, v65
	v_exp_f32_e32 v198, v66
	v_exp_f32_e32 v199, v67
	v_exp_f32_e32 v200, v43
	v_exp_f32_e32 v201, v47
	v_exp_f32_e32 v202, v51
	v_exp_f32_e32 v203, v35
	v_add_co_u32_e32 v36, vcc, s5, v84
	v_add_f32_e32 v16, 0, v0
	s_nop 0
	v_addc_co_u32_e32 v37, vcc, 0, v85, vcc
	v_add_co_u32_e32 v38, vcc, s11, v84
	v_bfe_u32 v17, v0, 16, 1
	v_bfe_u32 v18, v4, 16, 1
	v_bfe_u32 v19, v8, 16, 1
	v_bfe_u32 v20, v12, 16, 1
	v_bfe_u32 v21, v111, 16, 1
	v_bfe_u32 v22, v156, 16, 1
	v_bfe_u32 v23, v157, 16, 1
	v_bfe_u32 v24, v158, 16, 1
	v_bfe_u32 v25, v159, 16, 1
	v_bfe_u32 v26, v160, 16, 1
	v_bfe_u32 v27, v161, 16, 1
	v_bfe_u32 v28, v162, 16, 1
	v_bfe_u32 v29, v163, 16, 1
	v_bfe_u32 v30, v164, 16, 1
	v_bfe_u32 v31, v165, 16, 1
	v_bfe_u32 v32, v166, 16, 1
	v_add_f32_e32 v33, 0, v1
	v_bfe_u32 v34, v1, 16, 1
	v_bfe_u32 v35, v5, 16, 1
	v_bfe_u32 v40, v9, 16, 1
	v_bfe_u32 v41, v13, 16, 1
	v_bfe_u32 v42, v167, 16, 1
	v_bfe_u32 v43, v168, 16, 1
	v_bfe_u32 v45, v170, 16, 1
	v_bfe_u32 v46, v171, 16, 1
	v_bfe_u32 v47, v172, 16, 1
	v_bfe_u32 v49, v174, 16, 1
	v_bfe_u32 v50, v175, 16, 1
	v_bfe_u32 v51, v177, 16, 1
	v_bfe_u32 v53, v179, 16, 1
	v_add_f32_e32 v54, 0, v2
	v_bfe_u32 v55, v2, 16, 1
	v_bfe_u32 v57, v10, 16, 1
	v_bfe_u32 v59, v180, 16, 1
	v_bfe_u32 v60, v181, 16, 1
	v_bfe_u32 v65, v186, 16, 1
	v_bfe_u32 v66, v187, 16, 1
	v_add_f32_e32 v71, 0, v3
	v_bfe_u32 v72, v3, 16, 1
	v_bfe_u32 v74, v11, 16, 1
	v_addc_co_u32_e32 v39, vcc, 0, v85, vcc
	v_bfe_u32 v44, v169, 16, 1
	v_bfe_u32 v48, v173, 16, 1
	v_bfe_u32 v52, v178, 16, 1
	v_bfe_u32 v56, v6, 16, 1
	v_bfe_u32 v58, v14, 16, 1
	v_bfe_u32 v61, v182, 16, 1
	v_bfe_u32 v62, v183, 16, 1
	v_bfe_u32 v63, v184, 16, 1
	v_bfe_u32 v64, v185, 16, 1
	v_bfe_u32 v67, v188, 16, 1
	v_bfe_u32 v68, v189, 16, 1
	v_bfe_u32 v69, v190, 16, 1
	v_bfe_u32 v70, v191, 16, 1
	v_bfe_u32 v73, v7, 16, 1
	v_bfe_u32 v75, v15, 16, 1
	v_bfe_u32 v76, v192, 16, 1
	v_bfe_u32 v77, v193, 16, 1
	v_bfe_u32 v78, v194, 16, 1
	v_bfe_u32 v79, v195, 16, 1
	v_bfe_u32 v80, v196, 16, 1
	v_bfe_u32 v81, v197, 16, 1
	v_bfe_u32 v82, v198, 16, 1
	v_bfe_u32 v83, v199, 16, 1
	v_bfe_u32 v84, v200, 16, 1
	v_bfe_u32 v85, v201, 16, 1
	v_bfe_u32 v86, v202, 16, 1
	v_bfe_u32 v87, v203, 16, 1
	v_add3_u32 v0, v0, v17, s10
	v_add_f32_e32 v16, v4, v16
	v_add3_u32 v4, v4, v18, s10
	v_add3_u32 v17, v8, v19, s10
	v_add3_u32 v18, v12, v20, s10
	v_add3_u32 v19, v111, v21, s10
	v_add3_u32 v20, v156, v22, s10
	v_add3_u32 v21, v157, v23, s10
	v_add3_u32 v22, v158, v24, s10
	v_add3_u32 v23, v159, v25, s10
	v_add3_u32 v24, v160, v26, s10
	v_add3_u32 v25, v161, v27, s10
	v_add3_u32 v26, v162, v28, s10
	v_add3_u32 v27, v163, v29, s10
	v_add3_u32 v28, v164, v30, s10
	v_add3_u32 v29, v165, v31, s10
	v_add3_u32 v30, v166, v32, s10
	v_add3_u32 v1, v1, v34, s10
	v_add_f32_e32 v31, v5, v33
	v_add3_u32 v5, v5, v35, s10
	v_add3_u32 v32, v9, v40, s10
	v_add3_u32 v33, v13, v41, s10
	v_add3_u32 v34, v167, v42, s10
	v_add3_u32 v35, v168, v43, s10
	v_add3_u32 v41, v170, v45, s10
	v_add3_u32 v42, v171, v46, s10
	v_add3_u32 v43, v172, v47, s10
	v_add3_u32 v45, v174, v49, s10
	v_add3_u32 v46, v175, v50, s10
	v_add3_u32 v47, v177, v51, s10
	v_add3_u32 v49, v179, v53, s10
	v_add3_u32 v2, v2, v55, s10
	v_add_f32_e32 v50, v6, v54
	v_add3_u32 v51, v10, v57, s10
	v_add3_u32 v53, v180, v59, s10
	v_add3_u32 v54, v181, v60, s10
	v_add3_u32 v59, v186, v65, s10
	v_add3_u32 v60, v187, v66, s10
	v_add3_u32 v3, v3, v72, s10
	v_add_f32_e32 v65, v7, v71
	v_add3_u32 v66, v11, v74, s10
	v_add3_u32 v40, v169, v44, s10
	v_add3_u32 v44, v173, v48, s10
	v_add3_u32 v48, v178, v52, s10
	v_add3_u32 v6, v6, v56, s10
	v_add3_u32 v52, v14, v58, s10
	v_add3_u32 v55, v182, v61, s10
	v_add3_u32 v56, v183, v62, s10
	v_add3_u32 v57, v184, v63, s10
	v_add3_u32 v58, v185, v64, s10
	v_add3_u32 v61, v188, v67, s10
	v_add3_u32 v62, v189, v68, s10
	v_add3_u32 v63, v190, v69, s10
	v_add3_u32 v64, v191, v70, s10
	v_add3_u32 v7, v7, v73, s10
	v_add3_u32 v67, v15, v75, s10
	v_add3_u32 v68, v192, v76, s10
	v_add3_u32 v69, v193, v77, s10
	v_add3_u32 v70, v194, v78, s10
	v_add3_u32 v71, v195, v79, s10
	v_add3_u32 v72, v196, v80, s10
	v_add3_u32 v73, v197, v81, s10
	v_add3_u32 v74, v198, v82, s10
	v_add3_u32 v75, v199, v83, s10
	v_add3_u32 v76, v200, v84, s10
	v_add3_u32 v77, v201, v85, s10
	v_add3_u32 v78, v202, v86, s10
	v_add3_u32 v79, v203, v87, s10
	ds_write_b16_d16_hi v109, v0
	ds_write_b16_d16_hi v109, v4 offset:32
	v_add_f32_e32 v0, v8, v16
	ds_write_b16_d16_hi v109, v17 offset:64
	ds_write_b16_d16_hi v109, v18 offset:96
	ds_write_b16_d16_hi v109, v19 offset:128
	ds_write_b16_d16_hi v109, v20 offset:160
	ds_write_b16_d16_hi v109, v21 offset:192
	ds_write_b16_d16_hi v109, v22 offset:224
	ds_write_b16_d16_hi v109, v23 offset:256
	ds_write_b16_d16_hi v109, v24 offset:288
	ds_write_b16_d16_hi v109, v25 offset:320
	ds_write_b16_d16_hi v109, v26 offset:352
	ds_write_b16_d16_hi v109, v27 offset:384
	ds_write_b16_d16_hi v109, v28 offset:416
	ds_write_b16_d16_hi v109, v29 offset:448
	ds_write_b16_d16_hi v109, v30 offset:480
	ds_write_b16_d16_hi v109, v1 offset:528
	ds_write_b16_d16_hi v109, v5 offset:560
	v_add_f32_e32 v1, v9, v31
	ds_write_b16_d16_hi v109, v32 offset:592
	ds_write_b16_d16_hi v109, v33 offset:624
	ds_write_b16_d16_hi v109, v34 offset:656
	ds_write_b16_d16_hi v109, v35 offset:688
	ds_write_b16_d16_hi v109, v40 offset:720
	ds_write_b16_d16_hi v109, v41 offset:752
	ds_write_b16_d16_hi v109, v42 offset:784
	ds_write_b16_d16_hi v109, v43 offset:816
	ds_write_b16_d16_hi v109, v44 offset:848
	ds_write_b16_d16_hi v109, v45 offset:880
	ds_write_b16_d16_hi v109, v46 offset:912
	ds_write_b16_d16_hi v109, v47 offset:944
	ds_write_b16_d16_hi v109, v48 offset:976
	ds_write_b16_d16_hi v109, v49 offset:1008
	ds_write_b16_d16_hi v109, v2 offset:1056
	ds_write_b16_d16_hi v109, v6 offset:1088
	v_add_f32_e32 v2, v10, v50
	ds_write_b16_d16_hi v109, v51 offset:1120
	ds_write_b16_d16_hi v109, v52 offset:1152
	ds_write_b16_d16_hi v109, v53 offset:1184
	ds_write_b16_d16_hi v109, v54 offset:1216
	ds_write_b16_d16_hi v109, v55 offset:1248
	ds_write_b16_d16_hi v109, v56 offset:1280
	ds_write_b16_d16_hi v109, v57 offset:1312
	ds_write_b16_d16_hi v109, v58 offset:1344
	ds_write_b16_d16_hi v109, v59 offset:1376
	ds_write_b16_d16_hi v109, v60 offset:1408
	ds_write_b16_d16_hi v109, v61 offset:1440
	ds_write_b16_d16_hi v109, v62 offset:1472
	ds_write_b16_d16_hi v109, v63 offset:1504
	ds_write_b16_d16_hi v109, v64 offset:1536
	ds_write_b16_d16_hi v109, v3 offset:1584
	ds_write_b16_d16_hi v109, v7 offset:1616
	v_add_f32_e32 v3, v11, v65
	ds_write_b16_d16_hi v109, v66 offset:1648
	ds_write_b16_d16_hi v109, v67 offset:1680
	ds_write_b16_d16_hi v109, v68 offset:1712
	ds_write_b16_d16_hi v109, v69 offset:1744
	ds_write_b16_d16_hi v109, v70 offset:1776
	ds_write_b16_d16_hi v109, v71 offset:1808
	ds_write_b16_d16_hi v109, v72 offset:1840
	ds_write_b16_d16_hi v109, v73 offset:1872
	ds_write_b16_d16_hi v109, v74 offset:1904
	ds_write_b16_d16_hi v109, v75 offset:1936
	ds_write_b16_d16_hi v109, v76 offset:1968
	ds_write_b16_d16_hi v109, v77 offset:2000
	ds_write_b16_d16_hi v109, v78 offset:2032
	ds_write_b16_d16_hi v109, v79 offset:2064
	v_add_f32_e32 v204, v12, v0
	v_add_f32_e32 v205, v13, v1
	v_add_f32_e32 v206, v14, v2
	v_add_f32_e32 v207, v15, v3
	ds_read_b128 v[0:3], v104
	ds_read_b128 v[4:7], v104 offset:64
	ds_read_b128 v[8:11], v97 offset:36864
	ds_read_b128 v[12:15], v97 offset:36928
	ds_read_b128 v[16:19], v110 offset:36864
	ds_read_b128 v[20:23], v110 offset:36928
	ds_read_b128 v[24:27], v110 offset:45312
	ds_read_b128 v[28:31], v110 offset:45376
	ds_read_b128 v[32:35], v110 offset:53760
	ds_read_b128 v[40:43], v110 offset:53824
	ds_read_b128 v[44:47], v110 offset:36992
	ds_read_b128 v[48:51], v110 offset:53888
	ds_read_b128 v[52:55], v104 offset:128
	ds_read_b128 v[56:59], v104 offset:192
	ds_read_b128 v[60:63], v97 offset:36992
	ds_read_b128 v[64:67], v97 offset:37056
	s_waitcnt lgkmcnt(13)
	v_mfma_f32_16x16x32_bf16 v[8:11], v[0:3], v[8:11], 0
	ds_read_b128 v[68:71], v110 offset:37056
	ds_read_b128 v[72:75], v110 offset:45440
	ds_read_b128 v[76:79], v110 offset:45504
	ds_read_b128 v[80:83], v110 offset:53952
	ds_read_b128 v[84:87], v104 offset:256
	ds_read_b128 v[88:91], v110 offset:37120
	ds_read_b128 v[92:95], v104 offset:320
	ds_read_b128 v[112:115], v97 offset:37120
	ds_read_b128 v[116:119], v97 offset:37184
	s_waitcnt lgkmcnt(14)
	v_mfma_f32_16x16x32_bf16 v[16:19], v[0:3], v[16:19], 0
	v_cmp_lt_i32_e32 vcc, s12, v96
	v_lshl_add_u64 v[100:101], v[100:101], 0, s[2:3]
	s_or_b64 s[8:9], vcc, s[8:9]
	v_mfma_f32_16x16x32_bf16 v[24:27], v[0:3], v[24:27], 0
	v_mfma_f32_16x16x32_bf16 v[0:3], v[0:3], v[32:35], 0
	ds_read_b128 v[32:35], v110 offset:37184
	ds_read_b128 v[120:123], v110 offset:45568
	ds_read_b128 v[124:127], v110 offset:45632
	v_mfma_f32_16x16x32_bf16 v[8:11], v[4:7], v[12:15], v[8:11]
	ds_read_b128 v[12:15], v110 offset:54016
	ds_read_b128 v[128:131], v110 offset:54080
	ds_read_b128 v[132:135], v97 offset:37248
	v_mfma_f32_16x16x32_bf16 v[16:19], v[4:7], v[20:23], v[16:19]
	ds_read_b128 v[20:23], v110 offset:45696
	ds_read_b128 v[136:139], v104 offset:384
	ds_read_b128 v[140:143], v104 offset:448
	v_mfma_f32_16x16x32_bf16 v[24:27], v[4:7], v[28:31], v[24:27]
	ds_read_b128 v[28:31], v97 offset:37312
	ds_read_b128 v[144:147], v110 offset:37248
	ds_read_b128 v[148:151], v110 offset:37312
	v_mfma_f32_16x16x32_bf16 v[0:3], v[4:7], v[40:43], v[0:3]
	ds_read_b128 v[4:7], v110 offset:45760
	ds_read_b128 v[40:43], v110 offset:54144
	ds_read_b128 v[152:155], v110 offset:54208
	s_nop 0
	s_waitcnt lgkmcnt(14)
	v_mfma_f32_16x16x32_bf16 v[8:11], v[52:55], v[60:63], v[8:11]
	v_add_f32_e32 v60, v111, v204
	v_add_f32_e32 v61, v167, v205
	v_mfma_f32_16x16x32_bf16 v[16:19], v[52:55], v[44:47], v[16:19]
	v_add_f32_e32 v44, v180, v206
	v_add_f32_e32 v45, v192, v207
	v_add_f32_e32 v46, v156, v60
	v_mfma_f32_16x16x32_bf16 v[24:27], v[52:55], v[72:75], v[24:27]
	v_add_f32_e32 v47, v168, v61
	v_add_f32_e32 v44, v181, v44
	v_add_f32_e32 v45, v193, v45
	v_mfma_f32_16x16x32_bf16 v[0:3], v[52:55], v[48:51], v[0:3]
	v_add_f32_e32 v46, v157, v46
	v_add_f32_e32 v47, v169, v47
	v_add_f32_e32 v44, v182, v44
	v_mfma_f32_16x16x32_bf16 v[8:11], v[56:59], v[64:67], v[8:11]
	v_add_f32_e32 v45, v194, v45
	v_add_f32_e32 v46, v158, v46
	v_add_f32_e32 v47, v170, v47
	v_mfma_f32_16x16x32_bf16 v[16:19], v[56:59], v[68:71], v[16:19]
	v_add_f32_e32 v44, v183, v44
	v_add_f32_e32 v45, v195, v45
	v_add_f32_e32 v46, v159, v46
	v_mfma_f32_16x16x32_bf16 v[24:27], v[56:59], v[76:79], v[24:27]
	v_add_f32_e32 v47, v171, v47
	v_add_f32_e32 v44, v184, v44
	v_add_f32_e32 v45, v196, v45
	v_mfma_f32_16x16x32_bf16 v[0:3], v[56:59], v[80:83], v[0:3]
	v_add_f32_e32 v46, v160, v46
	v_add_f32_e32 v47, v172, v47
	v_add_f32_e32 v44, v185, v44
	v_mfma_f32_16x16x32_bf16 v[8:11], v[84:87], v[112:115], v[8:11]
	v_add_f32_e32 v45, v197, v45
	v_add_f32_e32 v46, v161, v46
	v_add_f32_e32 v47, v173, v47
	v_mfma_f32_16x16x32_bf16 v[16:19], v[84:87], v[88:91], v[16:19]
	v_add_f32_e32 v44, v186, v44
	v_add_f32_e32 v45, v198, v45
	v_add_f32_e32 v46, v162, v46
	s_waitcnt lgkmcnt(13)
	v_mfma_f32_16x16x32_bf16 v[24:27], v[84:87], v[120:123], v[24:27]
	v_add_f32_e32 v47, v174, v47
	v_add_f32_e32 v44, v187, v44
	v_add_f32_e32 v45, v199, v45
	s_waitcnt lgkmcnt(11)
	v_mfma_f32_16x16x32_bf16 v[0:3], v[84:87], v[12:15], v[0:3]
	v_add_f32_e32 v12, v163, v46
	v_add_f32_e32 v13, v175, v47
	v_add_f32_e32 v44, v188, v44
	v_mfma_f32_16x16x32_bf16 v[8:11], v[92:95], v[116:119], v[8:11]
	v_add_f32_e32 v45, v200, v45
	v_add_f32_e32 v46, v164, v12
	v_add_f32_e32 v47, v177, v13
	v_mfma_f32_16x16x32_bf16 v[12:15], v[92:95], v[32:35], v[16:19]
	v_add_f32_e32 v32, v189, v44
	v_add_f32_e32 v33, v201, v45
	v_add_f32_e32 v34, v165, v46
	v_mfma_f32_16x16x32_bf16 v[16:19], v[92:95], v[124:127], v[24:27]
	s_waitcnt lgkmcnt(10)
	v_mfma_f32_16x16x32_bf16 v[0:3], v[92:95], v[128:131], v[0:3]
	s_nop 0
	v_add_f32_e32 v24, v178, v47
	v_add_f32_e32 v25, v190, v32
	v_add_f32_e32 v26, v202, v33
	v_add_f32_e32 v27, v166, v34
	v_add_f32_e32 v24, v179, v24
	v_add_f32_e32 v25, v191, v25
	s_waitcnt lgkmcnt(7)
	v_mfma_f32_16x16x32_bf16 v[8:11], v[136:139], v[132:135], v[8:11]
	v_add_f32_e32 v26, v203, v26
	v_add_f32_dpp v27, v27, v27 row_ror:8 row_mask:0xf bank_mask:0xf bound_ctrl:1
	v_add_f32_dpp v24, v24, v24 row_ror:8 row_mask:0xf bank_mask:0xf bound_ctrl:1
	s_waitcnt lgkmcnt(4)
	v_mfma_f32_16x16x32_bf16 v[12:15], v[136:139], v[144:147], v[12:15]
	v_add_f32_dpp v25, v25, v25 row_ror:8 row_mask:0xf bank_mask:0xf bound_ctrl:1
	v_add_f32_dpp v26, v26, v26 row_ror:8 row_mask:0xf bank_mask:0xf bound_ctrl:1
	v_add_f32_dpp v27, v27, v27 row_ror:4 row_mask:0xf bank_mask:0xf bound_ctrl:1
	v_mfma_f32_16x16x32_bf16 v[16:19], v[136:139], v[20:23], v[16:19]
	v_add_f32_dpp v20, v24, v24 row_ror:4 row_mask:0xf bank_mask:0xf bound_ctrl:1
	v_add_f32_dpp v21, v25, v25 row_ror:4 row_mask:0xf bank_mask:0xf bound_ctrl:1
	v_add_f32_dpp v22, v26, v26 row_ror:4 row_mask:0xf bank_mask:0xf bound_ctrl:1
	s_waitcnt lgkmcnt(1)
	v_mfma_f32_16x16x32_bf16 v[0:3], v[136:139], v[40:43], v[0:3]
	v_add_f32_dpp v23, v27, v27 row_ror:2 row_mask:0xf bank_mask:0xf bound_ctrl:1
	v_add_f32_dpp v20, v20, v20 row_ror:2 row_mask:0xf bank_mask:0xf bound_ctrl:1
	v_add_f32_dpp v21, v21, v21 row_ror:2 row_mask:0xf bank_mask:0xf bound_ctrl:1
	v_add_f32_dpp v22, v22, v22 row_ror:2 row_mask:0xf bank_mask:0xf bound_ctrl:1
	v_add_f32_dpp v23, v23, v23 row_ror:1 row_mask:0xf bank_mask:0xf bound_ctrl:1
	v_mfma_f32_16x16x32_bf16 v[8:11], v[140:143], v[28:31], v[8:11]
	v_add_f32_dpp v20, v20, v20 row_ror:1 row_mask:0xf bank_mask:0xf bound_ctrl:1
	v_add_f32_dpp v21, v21, v21 row_ror:1 row_mask:0xf bank_mask:0xf bound_ctrl:1
	v_add_f32_dpp v22, v22, v22 row_ror:1 row_mask:0xf bank_mask:0xf bound_ctrl:1
	v_rcp_f32_e32 v23, v23
	v_mfma_f32_16x16x32_bf16 v[12:15], v[140:143], v[148:151], v[12:15]
	s_nop 2
	v_mul_f32_e32 v8, v23, v8
	v_mfma_f32_16x16x32_bf16 v[4:7], v[140:143], v[4:7], v[16:19]
	s_nop 2
	v_rcp_f32_e32 v16, v20
	v_rcp_f32_e32 v17, v21
	v_rcp_f32_e32 v18, v22
	s_waitcnt lgkmcnt(0)
	v_mfma_f32_16x16x32_bf16 v[0:3], v[140:143], v[152:155], v[0:3]
	v_mul_f32_e32 v9, v16, v9
	v_mul_f32_e32 v10, v17, v10
	v_mul_f32_e32 v11, v18, v11
	v_mul_f32_e32 v12, v23, v12
	v_mul_f32_e32 v13, v16, v13
	v_mul_f32_e32 v14, v17, v14
	v_mul_f32_e32 v15, v18, v15
	v_mul_f32_e32 v4, v23, v4
	v_mul_f32_e32 v5, v16, v5
	v_mul_f32_e32 v6, v17, v6
	v_mul_f32_e32 v7, v18, v7
	v_mul_f32_e32 v0, v23, v0
	v_mul_f32_e32 v1, v16, v1
	v_mul_f32_e32 v2, v17, v2
	v_mul_f32_e32 v3, v18, v3
	v_bfe_u32 v16, v8, 16, 1
	v_bfe_u32 v17, v9, 16, 1
	v_bfe_u32 v18, v10, 16, 1
	v_bfe_u32 v19, v11, 16, 1
	v_bfe_u32 v20, v12, 16, 1
	v_bfe_u32 v21, v13, 16, 1
	v_bfe_u32 v22, v14, 16, 1
	v_bfe_u32 v23, v15, 16, 1
	v_bfe_u32 v24, v4, 16, 1
	v_bfe_u32 v25, v5, 16, 1
	v_bfe_u32 v26, v6, 16, 1
	v_bfe_u32 v27, v7, 16, 1
	v_bfe_u32 v28, v0, 16, 1
	v_bfe_u32 v29, v1, 16, 1
	v_bfe_u32 v30, v2, 16, 1
	v_bfe_u32 v31, v3, 16, 1
	v_add3_u32 v8, v8, v16, s10
	v_add3_u32 v9, v9, v17, s10
	v_add3_u32 v10, v10, v18, s10
	v_add3_u32 v11, v11, v19, s10
	v_add3_u32 v12, v12, v20, s10
	v_add3_u32 v13, v13, v21, s10
	v_add3_u32 v14, v14, v22, s10
	v_add3_u32 v15, v15, v23, s10
	v_add3_u32 v4, v4, v24, s10
	v_add3_u32 v5, v5, v25, s10
	v_add3_u32 v6, v6, v26, s10
	v_add3_u32 v7, v7, v27, s10
	v_add3_u32 v0, v0, v28, s10
	v_add3_u32 v1, v1, v29, s10
	v_add3_u32 v2, v2, v30, s10
	v_add3_u32 v3, v3, v31, s10
	s_andn2_b64 vcc, exec, s[8:9]
	s_cbranch_vccz .Lma_nopf_b
	v_lshl_add_u64 v[240:241], v[100:101], 0, v[98:99]
	v_add_co_u32_e32 v240, vcc, 0x1b400000, v240
	s_nop 1
	v_addc_co_u32_e32 v241, vcc, 0, v241, vcc
	global_load_dwordx4 v[232:235], v[240:241], off offset:1536
	global_load_dwordx4 v[236:239], v[240:241], off offset:1600
.Lma_nopf_b:
	global_store_short_d16_hi v[36:37], v8, off offset:1536
	global_store_short_d16_hi v[36:37], v9, off offset:3584
	global_store_short_d16_hi v[38:39], v10, off offset:1536
	global_store_short_d16_hi v[38:39], v11, off offset:3584
	global_store_short_d16_hi v[36:37], v12, off offset:1568
	global_store_short_d16_hi v[36:37], v13, off offset:3616
	global_store_short_d16_hi v[38:39], v14, off offset:1568
	global_store_short_d16_hi v[38:39], v15, off offset:3616
	global_store_short_d16_hi v[36:37], v4, off offset:1600
	global_store_short_d16_hi v[36:37], v5, off offset:3648
	global_store_short_d16_hi v[38:39], v6, off offset:1600
	global_store_short_d16_hi v[38:39], v7, off offset:3648
	global_store_short_d16_hi v[36:37], v0, off offset:1632
	global_store_short_d16_hi v[36:37], v1, off offset:3680
	global_store_short_d16_hi v[38:39], v2, off offset:1632
	global_store_short_d16_hi v[38:39], v3, off offset:3680
	s_andn2_b64 exec, exec, s[8:9]
	s_cbranch_execnz .LBB0_2093
